# P2 (conv mixer + latent norms + rope tables) moved into idle workgroups of the in-proj GEMM tail behind a counter hand-off; win_t/u1 relocated; barrier 2 removed; early buffer_inv
# speedup vs baseline: 1.0061x; 1.0016x over previous
; __device__ __forceinline__ void tr_load(const TJob& j, f32x4 (&v)[16], int lane) {
;     const int nq = lane & 15, kr = lane >> 4;
;     const float* src = j.W + (size_t)(64 * j.kb + kr) * j.N + 64 * j.nb + 4 * nq;
; #pragma unroll
;     for (int i = 0; i < 16; ++i) v[i] = __builtin_nontemporal_load((const f32x4*)(src + (size_t)(4 * i) * j.N));
; }
; __global__ void __launch_bounds__(NWAVES * 64, 2) fwd_kernel(Args a) {
;     ...
;             f32x4 va[16], vb[16]; int it = gw;
;             if (it < I_IN) { TJob ja = job0(it, a.in[3], a.in[6], a.in[8], a.in[10], a.in[13], a.in[14], win_t, wc_t, qb_t, kvb_t, mla_t, wo_t); tr_load(ja, va, lane);
;                 for (;;) {
;                     const int itb = it + NGW; TJob jb; const bool hb = itb < I_IN; if (hb) { jb = job0(itb, a.in[3], a.in[6], a.in[8], a.in[10], a.in[13], a.in[14], win_t, wc_t, qb_t, kvb_t, mla_t, wo_t); tr_load(jb, vb, lane); }
;                     tr_store(ja, va, scr, lane); if (!hb) break;
;                     const int itc = itb + NGW; const bool hc = itc < I_IN; if (hc) { ja = job0(itc, a.in[3], a.in[6], a.in[8], a.in[10], a.in[13], a.in[14], win_t, wc_t, qb_t, kvb_t, mla_t, wo_t); tr_load(ja, va, lane); }
.LBB0_6:
	s_or_b64 exec, exec, s[6:7]
	s_lshl_b32 s12, s68, 3
	v_mov_b32_e32 v131, v226
	s_add_u32 s14, s30, 0xe600000
	s_addc_u32 s15, s31, 0
	v_readfirstlane_b32 s3, v131
	s_ashr_i32 s13, s3, 6
	s_lshl_b32 s90, s95, 3
	v_and_b32_e32 v1, 63, v131
	s_add_i32 s3, s13, s90
	s_cmpk_gt_i32 s3, 0x109f
	v_lshlrev_b32_e32 v130, 3, v1
	s_cbranch_scc1 .LBB0_15
	s_mul_i32 s6, s13, 0x4100
	s_add_i32 s34, s6, 0
	s_mul_hi_i32 s6, s3, 0xf6603d99
	s_add_i32 s6, s6, s3
	s_lshr_b32 s7, s6, 31
	s_ashr_i32 s6, s6, 7
	s_add_i32 s10, s6, s7
	s_mul_i32 s6, s10, 0x85
	s_sub_i32 s7, s3, s6
	s_lshl_b32 s6, s7, 6
	s_sub_i32 s8, s6, 64
	s_cmpk_lg_i32 s7, 0x44
	v_lshrrev_b32_e32 v133, 4, v1
	s_cselect_b32 s8, s8, 0x2100
	s_cmpk_lt_i32 s7, 0x44
	v_lshl_or_b32 v4, s10, 6, v133
	s_mov_b32 s11, 0x8500
	v_mov_b64_e32 v[2:3], s[58:59]
	s_cselect_b32 s16, s6, s8
	v_mad_i64_i32 v[2:3], s[8:9], v4, s11, v[2:3]
	v_lshlrev_b32_e32 v4, 2, v1
	s_ashr_i32 s7, s6, 31
	v_and_b32_e32 v132, 60, v4
	v_lshl_add_u64 v[2:3], s[6:7], 2, v[2:3]
	v_mov_b32_e32 v135, 0
	v_lshlrev_b32_e32 v134, 2, v132
	v_lshl_add_u64 v[18:19], v[2:3], 0, v[134:135]
	s_mov_b32 s17, 0x21000
	v_add_co_u32_e32 v6, vcc, s17, v18
	s_mov_b32 s18, 0x42000
	s_nop 0
	v_addc_co_u32_e32 v7, vcc, 0, v19, vcc
	v_add_co_u32_e32 v10, vcc, s18, v18
	s_mov_b32 s19, 0x63000
	s_nop 0
	v_addc_co_u32_e32 v11, vcc, 0, v19, vcc
	v_add_co_u32_e32 v14, vcc, s19, v18
	s_mov_b32 s20, 0x85000
	s_nop 0
	v_addc_co_u32_e32 v15, vcc, 0, v19, vcc
	v_add_co_u32_e32 v20, vcc, s20, v18
	s_mov_b32 s21, 0xa6000
	s_nop 0
	v_addc_co_u32_e32 v21, vcc, 0, v19, vcc
	v_add_co_u32_e32 v22, vcc, s21, v18
	s_mov_b32 s22, 0xc7000
	s_nop 0
	v_addc_co_u32_e32 v23, vcc, 0, v19, vcc
	v_add_co_u32_e32 v26, vcc, s22, v18
	s_mov_b32 s23, 0xe8000
	s_nop 0
	v_addc_co_u32_e32 v27, vcc, 0, v19, vcc
	v_add_co_u32_e32 v28, vcc, s23, v18
	s_mov_b32 s24, 0x10a000
	s_nop 0
	v_addc_co_u32_e32 v29, vcc, 0, v19, vcc
	v_add_co_u32_e32 v30, vcc, s24, v18
	s_mov_b32 s25, 0x12b000
	s_nop 0
	v_addc_co_u32_e32 v31, vcc, 0, v19, vcc
	v_add_co_u32_e32 v32, vcc, s25, v18
	s_mov_b32 s26, 0x14c000
	s_nop 0
	v_addc_co_u32_e32 v33, vcc, 0, v19, vcc
	v_add_co_u32_e32 v42, vcc, s26, v18
	s_mov_b32 s27, 0x16d000
	s_nop 0
	v_addc_co_u32_e32 v43, vcc, 0, v19, vcc
	v_add_co_u32_e32 v44, vcc, s27, v18
	s_mov_b32 s33, 0x18f000
	s_nop 0
	v_addc_co_u32_e32 v45, vcc, 0, v19, vcc
	v_add_co_u32_e32 v46, vcc, s33, v18
	s_mov_b32 s6, 0x1b0000
	s_nop 0
	v_addc_co_u32_e32 v47, vcc, 0, v19, vcc
	v_add_co_u32_e32 v48, vcc, s6, v18
	s_mov_b32 s6, 0x1d1000
	s_nop 0
	v_addc_co_u32_e32 v49, vcc, 0, v19, vcc
	v_add_co_u32_e32 v58, vcc, s6, v18
	s_mov_b32 s6, 0x1f2000
	s_nop 0
	v_addc_co_u32_e32 v59, vcc, 0, v19, vcc
	v_add_co_u32_e32 v60, vcc, s6, v18
	global_load_dwordx4 v[2:5], v[18:19], off nt
	s_nop 0
	global_load_dwordx4 v[6:9], v[6:7], off offset:1024 nt
	s_nop 0
	global_load_dwordx4 v[10:13], v[10:11], off offset:2048 nt
	s_nop 0
	global_load_dwordx4 v[14:17], v[14:15], off offset:3072 nt
	v_addc_co_u32_e32 v61, vcc, 0, v19, vcc
	global_load_dwordx4 v[18:21], v[20:21], off nt
	s_nop 0
	global_load_dwordx4 v[22:25], v[22:23], off offset:1024 nt
	s_nop 0
	global_load_dwordx4 v[34:37], v[26:27], off offset:2048 nt
	global_load_dwordx4 v[38:41], v[28:29], off offset:3072 nt
	global_load_dwordx4 v[50:53], v[30:31], off nt
	global_load_dwordx4 v[54:57], v[32:33], off offset:1024 nt
	global_load_dwordx4 v[66:69], v[42:43], off offset:2048 nt
	global_load_dwordx4 v[70:73], v[44:45], off offset:3072 nt
	global_load_dwordx4 v[82:85], v[46:47], off nt
	global_load_dwordx4 v[86:89], v[48:49], off offset:1024 nt
	global_load_dwordx4 v[98:101], v[58:59], off offset:2048 nt
	global_load_dwordx4 v[102:105], v[60:61], off offset:3072 nt
	v_lshrrev_b32_e32 v136, 3, v1
	v_and_b32_e32 v26, 56, v130
	v_add_u32_e32 v27, s34, v134
	v_mul_u32_u24_e32 v28, 0x104, v133
	v_mul_u32_u24_e32 v29, 0x104, v26
	v_lshlrev_b32_e32 v30, 2, v136
	v_add3_u32 v137, s34, v29, v30
	v_or_b32_e32 v138, 8, v136
	v_or_b32_e32 v139, 16, v136
	v_or_b32_e32 v140, 24, v136
	v_or_b32_e32 v141, 32, v136
	v_or_b32_e32 v142, 40, v136
	v_or_b32_e32 v143, 48, v136
	v_lshlrev_b32_e32 v134, 1, v26
	v_or_b32_e32 v144, 56, v136
	v_add_u32_e32 v145, v27, v28
	s_mov_b32 s36, s3
	s_branch .LBB0_10

; __global__ void __launch_bounds__(NWAVES * 64, 2) fwd_kernel(Args a) {
;     ...
;         { v4u* p = (v4u*)(win_t + (size_t)INW * DM); const int n16 = (INWP - INW) * DM * 2 / 16; const v4u z = {0u, 0u, 0u, 0u};
;           for (int i = (vcu * NWAVES * 64) + tid; i < n16; i += G * NWAVES * 64) p[i] = z;
;           constexpr int PR16 = 64 * QL * 2 / 16;
;           for (int i = (vcu * NWAVES * 64) + tid; i < NHEAD * PR16; i += G * NWAVES * 64) ((v4u*)(qb_t + (size_t)(256 * (i / PR16) + 192) * QL))[i % PR16] = z; }
.LBB0_15:
	s_waitcnt vmcnt(22)
	v_lshl_add_u32 v6, s95, 9, v131
	s_mov_b32 s6, 0xc000
	v_cmp_gt_i32_e32 vcc, s6, v6
	s_and_saveexec_b64 s[6:7], vcc
	s_cbranch_execz .LBB0_18
	v_ashrrev_i32_e32 v7, 31, v6
	s_lshl_b32 s8, s68, 9
	v_lshl_add_u64 v[2:3], v[6:7], 4, s[30:31]
	s_mov_b64 s[10:11], 0x10740000
	v_lshl_add_u64 v[8:9], v[2:3], 0, s[10:11]
	s_ashr_i32 s9, s8, 31
	v_mov_b32_e32 v2, 0
	s_lshl_b64 s[10:11], s[8:9], 4
	s_mov_b64 s[16:17], 0
	v_mov_b32_e32 v3, v2
	v_mov_b32_e32 v4, v2
	v_mov_b32_e32 v5, v2
	s_mov_b32 s9, 0xbfff
	v_mov_b32_e32 v7, v6

; __device__ __forceinline__ unsigned pk2(float lo, float hi) { return pg8::cvt_pk_bf16(lo, hi); }
; __device__ __forceinline__ void rms_row_2048(const float* xrow, const float* g, bf16* orow, int lane) {
;     const f32x4* xr = (const f32x4*)xrow + lane; const f32x4* gr = (const f32x4*)g + lane;
;     f32x4 v[8]; float s = 0.f;
; #pragma unroll
;     for (int j = 0; j < 8; ++j) { v[j] = __builtin_nontemporal_load(xr + 64 * j); s += (v[j].x * v[j].x + v[j].y * v[j].y) + (v[j].z * v[j].z + v[j].w * v[j].w); }
;     const float r = rsqrtf(wave_sum(s) * (1.f / 2048.f) + EPS);
;     v2u* o8 = (v2u*)orow + lane;
; #pragma unroll
;     for (int j = 0; j < 8; ++j) { const f32x4 gg = gr[64 * j]; v2u o; o.x = pk2(v[j].x * r * gg.x, v[j].y * r * gg.y); o.y = pk2(v[j].z * r * gg.z, v[j].w * r * gg.w); o8[64 * j] = o; }
; }
.LBB0_21:
	s_or_b64 exec, exec, s[0:1]
	s_cmpk_gt_i32 s3, 0x1fff
	v_mbcnt_lo_u32_b32 v147, -1, 0
	s_cbranch_scc1 .LBB0_24
	v_mbcnt_hi_u32_b32 v4, -1, v147
	v_lshlrev_b32_e32 v2, 4, v1
	v_and_b32_e32 v1, 64, v4
	v_add_u32_e32 v5, 64, v1
	v_xor_b32_e32 v1, 1, v4
	v_cmp_lt_i32_e32 vcc, v1, v5
	v_xor_b32_e32 v8, 2, v4
	s_ashr_i32 s7, s13, 31
	v_cndmask_b32_e32 v1, v4, v1, vcc
	v_cmp_lt_i32_e32 vcc, v8, v5
	s_ashr_i32 s8, s90, 31
	s_add_u32 s6, s13, s90
	v_cndmask_b32_e32 v8, v4, v8, vcc
	s_waitcnt vmcnt(19)
	v_lshlrev_b32_e32 v20, 2, v8
	v_xor_b32_e32 v8, 4, v4
	v_cmp_lt_i32_e32 vcc, v8, v5
	v_mov_b32_e32 v3, 0
	s_addc_u32 s7, s7, s8
	v_cndmask_b32_e32 v8, v4, v8, vcc
	v_lshlrev_b32_e32 v21, 2, v8
	v_xor_b32_e32 v8, 8, v4
	v_cmp_lt_i32_e32 vcc, v8, v5
	v_lshl_add_u64 v[6:7], s[56:57], 0, v[2:3]
	s_mov_b64 s[0:1], 0x1000
	v_cndmask_b32_e32 v8, v4, v8, vcc
	s_waitcnt vmcnt(18)
	v_lshlrev_b32_e32 v22, 2, v8
	v_xor_b32_e32 v8, 16, v4
	v_cmp_lt_i32_e32 vcc, v8, v5
	s_lshl_b64 s[8:9], s[6:7], 13
	s_add_u32 s8, s52, s8
	v_cndmask_b32_e32 v8, v4, v8, vcc
	v_lshlrev_b32_e32 v23, 2, v8
	v_xor_b32_e32 v8, 32, v4
	v_cmp_lt_i32_e32 vcc, v8, v5
	s_addc_u32 s9, s53, s9
	s_ashr_i32 s13, s12, 31
	v_cndmask_b32_e32 v4, v4, v8, vcc
	v_lshl_add_u64 v[8:9], v[6:7], 0, s[0:1]
	s_mov_b64 s[0:1], 0x1400
	v_lshl_add_u64 v[10:11], v[6:7], 0, s[0:1]
	s_mov_b64 s[0:1], 0x1800
	v_lshlrev_b32_e32 v24, 2, v4
	v_lshl_add_u64 v[12:13], v[6:7], 0, s[0:1]
	s_mov_b64 s[0:1], 0x1c00
	v_lshl_add_u64 v[4:5], s[8:9], 0, v[2:3]
	v_lshl_add_u64 v[14:15], v[6:7], 0, s[0:1]
	v_lshl_add_u64 v[16:17], v[4:5], 0, s[0:1]
	s_lshl_b64 s[0:1], s[12:13], 13
	s_lshl_b64 s[6:7], s[6:7], 12
	s_add_u32 s6, s30, s6
	v_mov_b32_e32 v131, v3
	s_addc_u32 s7, s31, s7
	v_lshl_add_u64 v[2:3], s[6:7], 0, v[130:131]
	s_mov_b64 s[6:7], 0x10800800
	v_lshlrev_b32_e32 v1, 2, v1
	v_lshl_add_u64 v[18:19], v[2:3], 0, s[6:7]
	s_lshl_b64 s[6:7], s[12:13], 12
	v_mov_b32_e32 v25, 0x358637bd
	s_mov_b32 s8, 0x800000

;     __device__ __forceinline__ int a_row(const Unit& u) const { return (u.pm / 17) * 4096 + 254 * (u.pm % 17) - 2; }
; #define PG8_STAGE(bufoff, gbase, voff) do { _Pragma("unroll") for (int _i = 0; _i < 2; ++_i) \
;         __builtin_amdgcn_global_load_lds((const unsigned*)((const char*)(gbase) + (voff)[_i]), (PG8_LAS unsigned*)(lds + (bufoff) + ldsw + _i * 8192), 16, 0, 0); } while (0)
; #define PG8_WAIT_V(n) asm volatile("s_waitcnt vmcnt(" #n ")" ::: "memory")
; #define PG8_BAR __builtin_amdgcn_s_barrier()
;     __host__ __device__ bool next(int i, Unit& u) const {
;         const long L = (long)i * G + c; if (L >= nwg) return false;
;         int wgid = (int)L; { const int q = nwg / NXCD, r = nwg % NXCD, xcd = wgid % NXCD, off = wgid / NXCD; wgid = (xcd < r ? xcd * (q + 1) : r * (q + 1) + (xcd - r) * q) + off; }
;         const int nig = WGM * nN, gid = wgid / nig, fm = gid * WGM, gsz = (nM - fm) < WGM ? (nM - fm) : WGM;
;         u.pm = fm + ((wgid % nig) % gsz); u.pn = (wgid % nig) / gsz; return true;
; template <class Epi, class Sched, bool ALIGN_EPI = false, bool SP2 = false>
; __device__ __forceinline__ void gemm_phase(PG8_LAS unsigned char* lds, const Gemm g, const Sched& S, const Epi& E) {
;     ...
;     const char* cA = (const char*)g.A + (long)S.a_row(cur) * (long)(K * 2); const char* cB = (const char*)g.Bt + (size_t)cur.pn * tstep;
;     S.a_ready(cur);
;     if constexpr (SP2) {
;         PG8_STAGE(PG8_SB(0, 0), cB, voffB); PG8_STAGE(PG8_SB(0, 1), cB + hstep, voffB); PG8_STAGE(PG8_SA(0, 0), cA, voffA); PG8_STAGE(PG8_SA(0, 1), cA + hstep, voffA);
;         if (wr == 1) PG8_BAR;
;         PG8_WAIT_V(2); PG8_BAR;
;         PG8_STAGE(PG8_SB(1, 0), cB + kstep, voffB); PG8_STAGE(PG8_SA(1, 0), cA + kstep, voffA); PG8_STAGE(PG8_SB(1, 1), cB + hstep + kstep, voffB);
;         PG8_WAIT_V(6); PG8_BAR;
;     } else {
;         PG8_STAGE(PG8_SB(0, 0), cB, voffB); PG8_STAGE(PG8_SA(0, 0), cA, voffA); PG8_STAGE(PG8_SB(0, 1), cB + hstep, voffB); PG8_STAGE(PG8_SA(0, 1), cA + hstep, voffA);
.LBB0_76:
	s_mov_b32 s100, 0
	s_nop 0
	v_writelane_b32 v255, s100, 6
	v_mov_b32_e32 v8, v226
	s_cmpk_lt_i32 s2, 0x440
	v_writelane_b32 v254, s68, 11
	s_cselect_b64 s[0:1], -1, 0
	s_cmpk_gt_i32 s2, 0x43f
	v_readfirstlane_b32 s56, v8
	v_writelane_b32 v254, s69, 12
	s_cbranch_scc1 .LBB0_78
	s_ashr_i32 s3, s2, 31
	s_lshr_b32 s3, s3, 29
	s_add_i32 s3, s2, s3
	s_ashr_i32 s4, s3, 3
	s_and_b32 s3, s3, -8
	s_sub_i32 s3, s2, s3
	s_cmp_lt_i32 s3, 0
	s_movk_i32 s5, 0x89
	s_cselect_b32 s5, s5, 0x88
	s_mul_i32 s3, s3, s5
	s_add_i32 s3, s3, s4
	s_mul_hi_i32 s4, s3, 0x78787879
	s_lshr_b32 s5, s4, 31
	s_ashr_i32 s4, s4, 6
	s_add_i32 s4, s4, s5
	s_lshl_b32 s5, s4, 2
	s_mulk_i32 s4, 0x88
	s_sub_i32 s3, s3, s4
	s_sext_i32_i16 s4, s3
	s_bfe_u32 s4, s4, 0x2001d
	s_add_i32 s4, s3, s4
	s_sext_i32_i16 s6, s4
	s_and_b32 s4, s4, 0xfffc
	s_sub_i32 s3, s3, s4
	s_sext_i32_i16 s3, s3
	s_add_i32 s97, s5, s3
	s_ashr_i32 s4, s6, 2
	s_add_i32 s4, s4, -1
	s_cmp_lt_i32 s4, 0
	s_cselect_b32 s4, 33, s4
.LBB0_78:
	s_add_u32 s10, s30, 0xa600000
	s_addc_u32 s11, s31, 0
	s_andn2_b64 vcc, exec, s[0:1]
	s_cbranch_vccnz .LBB0_148
	v_ashrrev_i32_e32 v1, 31, v8
	v_lshrrev_b32_e32 v1, 26, v1
	v_add_u32_e32 v1, v8, v1
	v_ashrrev_i32_e32 v9, 6, v1
	v_bfe_i32 v1, v8, 27, 1
	v_lshlrev_b32_e32 v0, 4, v8
	v_lshrrev_b32_e32 v1, 22, v1
	v_add_u32_e32 v1, v0, v1
	v_and_b32_e32 v1, 0xfffffc00, v1
	v_sub_u32_e32 v1, v0, v1
	v_lshrrev_b32_e32 v2, 4, v1
	v_bitop3_b32 v1, v2, v1, 32 bitop3:0x6c
	v_ashrrev_i32_e32 v3, 31, v1
	v_lshrrev_b32_e32 v3, 26, v3
	v_add_u32_e32 v3, v1, v3
	v_lshlrev_b32_e32 v2, 3, v9
	s_waitcnt vmcnt(21)
	v_ashrrev_i32_e32 v10, 6, v3
	v_and_b32_e32 v3, 0xc0, v3
	v_and_b32_e32 v2, -16, v2
	v_sub_u32_e32 v1, v1, v3
	v_mov_b32_e32 v3, 1
	v_add_u32_e32 v2, v10, v2
	v_ashrrev_i16_sdwa v1, v3, sext(v1) dst_sel:DWORD dst_unused:UNUSED_PAD src0_sel:DWORD src1_sel:BYTE_0
	v_lshlrev_b32_e32 v4, 5, v9
	v_bfe_i32 v11, v1, 0, 16
	v_lshlrev_b32_e32 v1, 1, v2
	v_lshrrev_b32_e32 v5, 2, v2
	v_and_b32_e32 v6, 3, v10
	s_mov_b32 s1, 0xfffe0
	v_and_b32_e32 v4, 32, v4
	v_and_b32_e32 v1, 24, v1
	v_and_b32_e32 v5, 4, v5
	v_and_or_b32 v6, v2, s1, v6
	v_or3_b32 v1, v6, v5, v1
	v_add_lshl_u32 v4, v4, v11, 1
	v_add_u32_e32 v0, 0x2000, v0
	v_lshl_add_u32 v138, v1, 12, v4
	v_ashrrev_i32_e32 v1, 31, v0
	v_lshrrev_b32_e32 v1, 22, v1
	v_add_u32_e32 v1, v0, v1
	v_ashrrev_i32_e32 v12, 10, v1
	v_mul_i32_i24_e32 v1, 0x400, v12
	v_sub_u32_e32 v0, v0, v1
	v_lshrrev_b32_e32 v1, 4, v0
	v_bitop3_b32 v0, v1, v0, 32 bitop3:0x6c
	v_lshl_add_u32 v136, v2, 12, v4
	v_ashrrev_i32_e32 v2, 31, v0
	v_lshrrev_b32_e32 v2, 26, v2
	v_add_u32_e32 v2, v0, v2
	v_lshlrev_b32_e32 v1, 3, v12
	v_ashrrev_i32_e32 v13, 6, v2
	v_and_b32_e32 v2, 0xc0, v2
	v_and_b32_e32 v1, -16, v1
	v_sub_u32_e32 v0, v0, v2
	s_ashr_i32 s0, s56, 6
	v_add_u32_e32 v1, v13, v1
	v_ashrrev_i16_sdwa v0, v3, sext(v0) dst_sel:DWORD dst_unused:UNUSED_PAD src0_sel:DWORD src1_sel:BYTE_0
	v_and_b32_e32 v3, 3, v13
	v_and_or_b32 v3, v1, s1, v3
	s_ashr_i32 s1, s56, 8
	s_lshl_b32 s3, s0, 10
	s_add_u32 s13, s30, 0x10800000
	s_addc_u32 s24, s31, 0
	s_lshl_b32 s6, s97, 8
	s_ashr_i32 s7, s6, 31
	s_ashr_i32 s5, s4, 31
	s_lshl_b64 s[6:7], s[6:7], 12
	s_lshl_b64 s[8:9], s[4:5], 20
	s_add_u32 s84, s14, s8
	v_lshlrev_b32_e32 v4, 5, v12
	s_waitcnt vmcnt(20)
	v_bfe_i32 v14, v0, 0, 16
	v_lshlrev_b32_e32 v0, 1, v1
	v_lshrrev_b32_e32 v2, 2, v1
	s_addc_u32 s85, s15, s9
	s_add_i32 s25, s3, 0
	v_and_b32_e32 v4, 32, v4
	v_and_b32_e32 v0, 24, v0
	v_and_b32_e32 v2, 4, v2
	s_add_i32 m0, s25, 0x10000
	v_or3_b32 v0, v3, v2, v0
	v_add_lshl_u32 v2, v4, v14, 1
	global_load_lds_dwordx4 v138, s[84:85]
	s_add_i32 m0, s25, 0x12000
	v_lshl_add_u32 v142, v0, 12, v2
	s_add_u32 s8, s84, 0x80000
	global_load_lds_dwordx4 v142, s[84:85]
	s_addc_u32 s9, s85, 0
	s_add_i32 m0, s25, 0x14000
	v_lshl_add_u32 v140, v1, 12, v2
	global_load_lds_dwordx4 v138, s[8:9]
	s_add_i32 m0, s25, 0x16000
	s_add_u32 s82, s13, s6
	s_addc_u32 s83, s24, s7
	s_add_i32 s33, s25, 0x2000
	global_load_lds_dwordx4 v142, s[8:9]
	s_mov_b32 m0, s25
	s_add_u32 s6, s82, 0x80000
	global_load_lds_dwordx4 v136, s[82:83]
	s_mov_b32 m0, s33
	s_addc_u32 s7, s83, 0
	s_add_i32 s34, s25, 0x4000
	global_load_lds_dwordx4 v140, s[82:83]
	s_mov_b32 m0, s34
	s_add_i32 s35, s25, 0x6000
	global_load_lds_dwordx4 v136, s[6:7]
	s_mov_b32 m0, s35
	v_mov_b32_e32 v145, 0
	global_load_lds_dwordx4 v140, s[6:7]
	v_mov_b32_e32 v139, v145
	v_mov_b32_e32 v143, v145
	v_mov_b32_e32 v137, v145
	v_mov_b32_e32 v141, v145
	s_cmp_eq_u32 s1, 1
	s_mov_b32 s68, 0
	v_lshl_add_u64 v[6:7], s[84:85], 0, v[138:139]
	v_lshl_add_u64 v[4:5], s[84:85], 0, v[142:143]
	v_lshl_add_u64 v[0:1], s[82:83], 0, v[136:137]
	s_cselect_b64 s[6:7], -1, 0
	s_cmp_lg_u32 s1, 1
	v_lshl_add_u64 v[2:3], s[82:83], 0, v[140:141]
	v_writelane_b32 v254, s90, 13
	s_cbranch_scc1 .LBB0_81
	s_barrier

;     __device__ __forceinline__ int a_row(const Unit& u) const { return (u.pm / 17) * 4096 + 254 * (u.pm % 17) - 2; }
;     __host__ __device__ bool next(int i, Unit& u) const {
;         const long L = (long)i * G + c; if (L >= nwg) return false;
;         int wgid = (int)L; { const int q = nwg / NXCD, r = nwg % NXCD, xcd = wgid % NXCD, off = wgid / NXCD; wgid = (xcd < r ? xcd * (q + 1) : r * (q + 1) + (xcd - r) * q) + off; }
;         const int nig = WGM * nN, gid = wgid / nig, fm = gid * WGM, gsz = (nM - fm) < WGM ? (nM - fm) : WGM;
;         u.pm = fm + ((wgid % nig) % gsz); u.pn = (wgid % nig) / gsz; return true;
; template <class Epi, class Sched, bool ALIGN_EPI = false, bool SP2 = false>
; __device__ __forceinline__ void gemm_phase(PG8_LAS unsigned char* lds, const Gemm g, const Sched& S, const Epi& E) {
;     ...
;         const bool has_next = S.next(ui + 1, nxt);
;         const char* nA = has_next ? (const char*)g.A + (long)S.a_row(nxt) * (long)(K * 2) : cA; const char* nB = has_next ? (const char*)g.Bt + (size_t)nxt.pn * tstep : cB;
.LBB0_84:
	s_add_i32 s68, s68, 1
	s_mul_i32 s0, s68, s71
	s_mul_hi_u32 s1, s68, s72
	s_add_i32 s1, s1, s0
	s_mul_i32 s0, s68, s72
	s_add_u32 s78, s0, s2
	s_addc_u32 s79, s1, s73
	v_cmp_gt_i64_e32 vcc, s[78:79], v[156:157]
	v_cmp_lt_i64_e64 s[0:1], s[78:79], v[154:155]
	s_cbranch_vccnz .LBB0_86
	s_ashr_i32 s5, s78, 31
	s_lshr_b32 s5, s5, 29
	s_add_i32 s5, s78, s5
	s_ashr_i32 s60, s5, 3
	s_and_b32 s5, s5, -8
	s_sub_i32 s5, s78, s5
	s_cmp_lt_i32 s5, 0
	s_movk_i32 s61, 0x89
	s_cselect_b32 s61, s61, 0x88
	s_mul_i32 s5, s5, s61
	s_add_i32 s5, s5, s60
	s_mul_hi_i32 s60, s5, 0x78787879
	s_lshr_b32 s61, s60, 31
	s_ashr_i32 s60, s60, 6
	s_add_i32 s60, s60, s61
	s_lshl_b32 s61, s60, 2
	s_sub_i32 s78, 32, s61
	s_min_i32 s78, s78, 4
	s_abs_i32 s79, s78
	v_cvt_f32_u32_e32 v0, s79
	s_sub_i32 s81, 0, s79
	s_mulk_i32 s60, 0x88
	s_sub_i32 s5, s5, s60
	v_rcp_iflag_f32_e32 v0, v0
	s_abs_i32 s60, s5
	s_xor_b32 s80, s5, s78
	s_ashr_i32 s80, s80, 31
	v_mul_f32_e32 v0, 0x4f7ffffe, v0
	v_cvt_u32_f32_e32 v0, v0
	s_nop 0
	v_readfirstlane_b32 s86, v0
	s_mul_i32 s81, s81, s86
	s_mul_hi_u32 s81, s86, s81
	s_add_i32 s86, s86, s81
	s_mul_hi_u32 s81, s60, s86
	s_mul_i32 s86, s81, s79
	s_sub_i32 s60, s60, s86
	s_add_i32 s87, s81, 1
	s_sub_i32 s86, s60, s79
	s_cmp_ge_u32 s60, s79
	s_cselect_b32 s81, s87, s81
	s_cselect_b32 s60, s86, s60
	s_add_i32 s86, s81, 1
	s_cmp_ge_u32 s60, s79
	s_cselect_b32 s60, s86, s81
	s_xor_b32 s60, s60, s80
	s_sub_i32 s60, s60, s80
	s_mul_i32 s78, s60, s78
	s_add_i32 s60, s60, -1
	s_cmp_lt_i32 s60, 0
	s_cselect_b32 s60, 33, s60
	s_sub_i32 s5, s5, s78
	s_add_i32 s96, s61, s5

; __device__ __forceinline__ unsigned cvt_pk_bf16(float lo, float hi) { unsigned r; asm volatile("v_cvt_pk_bf16_f32 %0, %1, %2" : "=v"(r) : "v"(lo), "v"(hi)); return r; }
; __device__ __forceinline__ float sigmoid_f(float x) { return __builtin_amdgcn_rcpf(1.0f + __builtin_amdgcn_exp2f(-1.4426950408889634f * x)); }
;     __device__ __forceinline__ void operator()(const f32x4 (&acc)[2][2][4][2], const Unit& u, int wr, int wc, int fr, int fq) const {
;     ...
;         const int row0 = u.pm * BM + wr * 64 + fr, c0 = wc * 32 + 8 * fq;
; #pragma unroll
;         for (int bj = 0; bj < 2; ++bj) {
;             const int c = c0 + bj * HALF;
;             if (mode == 2 && c >= 64) continue;
;             f32x4 b0 = (f32x4){0.f, 0.f, 0.f, 0.f}, b1 = b0;
;             if (mode == 1) { b0 = *(const f32x4*)(bgate + ct + c); b1 = *(const f32x4*)(bgate + ct + c + 4); }
; #pragma unroll
;             for (int ai = 0; ai < 2; ++ai)
; #pragma unroll
;                 for (int m = 0; m < 4; ++m) {
;                     f32x4 v0 = acc[ai][bj][m][0] + b0, v1 = acc[ai][bj][m][1] + b1;
;                     if (mode == 1) {
; #pragma unroll
;                         for (int e = 0; e < 4; ++e) { v0[e] = sigmoid_f(v0[e]); v1[e] = sigmoid_f(v1[e]); }
;                     }
;                     u32x4 w; w.x = cvt_pk_bf16(v0[0], v0[1]); w.y = cvt_pk_bf16(v0[2], v0[3]); w.z = cvt_pk_bf16(v1[0], v1[1]); w.w = cvt_pk_bf16(v1[2], v1[3]);
;                     *(u32x4*)(dst + (size_t)(row0 + ai * HALF + m * 16) * ldc + ct + c) = w;
;                 }
.LBB0_108:
	v_cvt_pk_bf16_f32 v124, v124, v125
	v_cvt_pk_bf16_f32 v125, v126, v127
	v_cvt_pk_bf16_f32 v126, v158, v159
	v_cvt_pk_bf16_f32 v127, v122, v123
	v_ashrrev_i32_e32 v122, 31, v165
	v_lshlrev_b32_e32 v144, 1, v146
	v_mul_lo_u32 v123, s83, v165
	v_mul_lo_u32 v122, s82, v122
	v_mad_u64_u32 v[158:159], s[90:91], s82, v165, 0
	v_lshl_add_u64 v[120:121], s[86:87], 0, v[144:145]
	v_add3_u32 v159, v159, v122, v123
	v_lshl_add_u64 v[158:159], v[158:159], 1, v[120:121]
	v_pk_add_f32 v[118:119], v[118:119], v[134:135]
	v_pk_add_f32 v[116:117], v[116:117], v[132:133]
	v_pk_add_f32 v[114:115], v[114:115], v[130:131]
	s_and_b64 vcc, exec, s[4:5]
	v_pk_add_f32 v[112:113], v[112:113], v[128:129]
	global_store_dwordx4 v[158:159], v[124:127], off sc1
	s_cbranch_vccnz .LBB0_110
	v_mul_f32_e32 v116, 0xbfb8aa3b, v116
	v_mul_f32_e32 v112, 0xbfb8aa3b, v112
	v_mul_f32_e32 v117, 0xbfb8aa3b, v117
	v_mul_f32_e32 v113, 0xbfb8aa3b, v113
	v_mul_f32_e32 v118, 0xbfb8aa3b, v118
	v_mul_f32_e32 v114, 0xbfb8aa3b, v114
	v_mul_f32_e32 v119, 0xbfb8aa3b, v119
	v_mul_f32_e32 v115, 0xbfb8aa3b, v115
	v_exp_f32_e32 v116, v116
	v_exp_f32_e32 v112, v112
	v_exp_f32_e32 v117, v117
	v_exp_f32_e32 v113, v113
	v_exp_f32_e32 v118, v118
	v_exp_f32_e32 v114, v114
	v_exp_f32_e32 v119, v119
	v_exp_f32_e32 v115, v115
	v_add_f32_e32 v116, 1.0, v116
	v_add_f32_e32 v112, 1.0, v112
	v_add_f32_e32 v117, 1.0, v117
	v_add_f32_e32 v113, 1.0, v113
	v_add_f32_e32 v118, 1.0, v118
	v_add_f32_e32 v114, 1.0, v114
	v_add_f32_e32 v119, 1.0, v119
	v_add_f32_e32 v115, 1.0, v115
	v_rcp_f32_e32 v116, v116
	v_rcp_f32_e32 v112, v112
	v_rcp_f32_e32 v117, v117
	v_rcp_f32_e32 v113, v113
	v_rcp_f32_e32 v118, v118
	v_rcp_f32_e32 v114, v114
	v_rcp_f32_e32 v119, v119
	v_rcp_f32_e32 v115, v115
.LBB0_110:
	v_cvt_pk_bf16_f32 v116, v116, v117
	v_cvt_pk_bf16_f32 v117, v118, v119
	v_cvt_pk_bf16_f32 v118, v112, v113
	v_or_b32_e32 v112, 16, v165
	v_cvt_pk_bf16_f32 v119, v114, v115
	v_mul_lo_u32 v114, s83, v112
	v_mad_u64_u32 v[112:113], s[90:91], s82, v112, 0
	v_add3_u32 v113, v113, v122, v114
	v_lshl_add_u64 v[112:113], v[112:113], 1, v[120:121]
	v_pk_add_f32 v[110:111], v[110:111], v[134:135]
	v_pk_add_f32 v[108:109], v[108:109], v[132:133]
	v_pk_add_f32 v[106:107], v[106:107], v[130:131]
	s_and_b64 vcc, exec, s[4:5]
	v_pk_add_f32 v[104:105], v[104:105], v[128:129]
	global_store_dwordx4 v[112:113], v[116:119], off sc1
	s_cbranch_vccnz .LBB0_112
	v_mul_f32_e32 v108, 0xbfb8aa3b, v108
	v_mul_f32_e32 v104, 0xbfb8aa3b, v104
	v_mul_f32_e32 v109, 0xbfb8aa3b, v109
	v_mul_f32_e32 v105, 0xbfb8aa3b, v105
	v_mul_f32_e32 v110, 0xbfb8aa3b, v110
	v_mul_f32_e32 v106, 0xbfb8aa3b, v106
	v_mul_f32_e32 v111, 0xbfb8aa3b, v111
	v_mul_f32_e32 v107, 0xbfb8aa3b, v107
	v_exp_f32_e32 v108, v108
	v_exp_f32_e32 v104, v104
	v_exp_f32_e32 v109, v109
	v_exp_f32_e32 v105, v105
	v_exp_f32_e32 v110, v110
	v_exp_f32_e32 v106, v106
	v_exp_f32_e32 v111, v111
	v_exp_f32_e32 v107, v107
	v_add_f32_e32 v108, 1.0, v108
	v_add_f32_e32 v104, 1.0, v104
	v_add_f32_e32 v109, 1.0, v109
	v_add_f32_e32 v105, 1.0, v105
	v_add_f32_e32 v110, 1.0, v110
	v_add_f32_e32 v106, 1.0, v106
	v_add_f32_e32 v111, 1.0, v111
	v_add_f32_e32 v107, 1.0, v107
	v_rcp_f32_e32 v108, v108
	v_rcp_f32_e32 v104, v104
	v_rcp_f32_e32 v109, v109
	v_rcp_f32_e32 v105, v105
	v_rcp_f32_e32 v110, v110
	v_rcp_f32_e32 v106, v106
	v_rcp_f32_e32 v111, v111
	v_rcp_f32_e32 v107, v107
.LBB0_112:
	v_cvt_pk_bf16_f32 v108, v108, v109
	v_cvt_pk_bf16_f32 v109, v110, v111
	v_cvt_pk_bf16_f32 v110, v104, v105
	v_or_b32_e32 v104, 32, v165
	v_cvt_pk_bf16_f32 v111, v106, v107
	v_mul_lo_u32 v106, s83, v104
	v_mad_u64_u32 v[104:105], s[90:91], s82, v104, 0
	v_add3_u32 v105, v105, v122, v106
	v_lshl_add_u64 v[104:105], v[104:105], 1, v[120:121]
	v_pk_add_f32 v[102:103], v[102:103], v[134:135]
	v_pk_add_f32 v[100:101], v[100:101], v[132:133]
	v_pk_add_f32 v[98:99], v[98:99], v[130:131]
	s_and_b64 vcc, exec, s[4:5]
	v_pk_add_f32 v[96:97], v[96:97], v[128:129]
	global_store_dwordx4 v[104:105], v[108:111], off sc1
	s_cbranch_vccnz .LBB0_114
	v_mul_f32_e32 v100, 0xbfb8aa3b, v100
	v_mul_f32_e32 v96, 0xbfb8aa3b, v96
	v_mul_f32_e32 v101, 0xbfb8aa3b, v101
	v_mul_f32_e32 v97, 0xbfb8aa3b, v97
	v_mul_f32_e32 v102, 0xbfb8aa3b, v102
	v_mul_f32_e32 v98, 0xbfb8aa3b, v98
	v_mul_f32_e32 v103, 0xbfb8aa3b, v103
	v_mul_f32_e32 v99, 0xbfb8aa3b, v99
	v_exp_f32_e32 v100, v100
	v_exp_f32_e32 v96, v96
	v_exp_f32_e32 v101, v101
	v_exp_f32_e32 v97, v97
	v_exp_f32_e32 v102, v102
	v_exp_f32_e32 v98, v98
	v_exp_f32_e32 v103, v103
	v_exp_f32_e32 v99, v99
	v_add_f32_e32 v100, 1.0, v100
	v_add_f32_e32 v96, 1.0, v96
	v_add_f32_e32 v101, 1.0, v101
	v_add_f32_e32 v97, 1.0, v97
	v_add_f32_e32 v102, 1.0, v102
	v_add_f32_e32 v98, 1.0, v98
	v_add_f32_e32 v103, 1.0, v103
	v_add_f32_e32 v99, 1.0, v99
	v_rcp_f32_e32 v100, v100
	v_rcp_f32_e32 v96, v96
	v_rcp_f32_e32 v101, v101
	v_rcp_f32_e32 v97, v97
	v_rcp_f32_e32 v102, v102
	v_rcp_f32_e32 v98, v98
	v_rcp_f32_e32 v103, v103
	v_rcp_f32_e32 v99, v99
; __device__ __forceinline__ unsigned cvt_pk_bf16(float lo, float hi) { unsigned r; asm volatile("v_cvt_pk_bf16_f32 %0, %1, %2" : "=v"(r) : "v"(lo), "v"(hi)); return r; }
; __device__ __forceinline__ float sigmoid_f(float x) { return __builtin_amdgcn_rcpf(1.0f + __builtin_amdgcn_exp2f(-1.4426950408889634f * x)); }
;     __device__ __forceinline__ void operator()(const f32x4 (&acc)[2][2][4][2], const Unit& u, int wr, int wc, int fr, int fq) const {
;     ...
;         const int row0 = u.pm * BM + wr * 64 + fr, c0 = wc * 32 + 8 * fq;
; #pragma unroll
;         for (int bj = 0; bj < 2; ++bj) {
;             const int c = c0 + bj * HALF;
;             if (mode == 2 && c >= 64) continue;
;             f32x4 b0 = (f32x4){0.f, 0.f, 0.f, 0.f}, b1 = b0;
;             if (mode == 1) { b0 = *(const f32x4*)(bgate + ct + c); b1 = *(const f32x4*)(bgate + ct + c + 4); }
; #pragma unroll
;             for (int ai = 0; ai < 2; ++ai)
; #pragma unroll
;                 for (int m = 0; m < 4; ++m) {
;                     f32x4 v0 = acc[ai][bj][m][0] + b0, v1 = acc[ai][bj][m][1] + b1;
;                     if (mode == 1) {
; #pragma unroll
;                         for (int e = 0; e < 4; ++e) { v0[e] = sigmoid_f(v0[e]); v1[e] = sigmoid_f(v1[e]); }
;                     }
;                     u32x4 w; w.x = cvt_pk_bf16(v0[0], v0[1]); w.y = cvt_pk_bf16(v0[2], v0[3]); w.z = cvt_pk_bf16(v1[0], v1[1]); w.w = cvt_pk_bf16(v1[2], v1[3]);
;                     *(u32x4*)(dst + (size_t)(row0 + ai * HALF + m * 16) * ldc + ct + c) = w;
;                 }
.LBB0_114:
	v_cvt_pk_bf16_f32 v100, v100, v101
	v_cvt_pk_bf16_f32 v101, v102, v103
	v_cvt_pk_bf16_f32 v102, v96, v97
	v_or_b32_e32 v96, 48, v165
	v_cvt_pk_bf16_f32 v103, v98, v99
	v_mul_lo_u32 v98, s83, v96
	v_mad_u64_u32 v[96:97], s[90:91], s82, v96, 0
	v_add3_u32 v97, v97, v122, v98
	v_lshl_add_u64 v[96:97], v[96:97], 1, v[120:121]
	v_pk_add_f32 v[94:95], v[94:95], v[134:135]
	v_pk_add_f32 v[92:93], v[92:93], v[132:133]
	v_pk_add_f32 v[90:91], v[90:91], v[130:131]
	s_and_b64 vcc, exec, s[4:5]
	v_pk_add_f32 v[88:89], v[88:89], v[128:129]
	global_store_dwordx4 v[96:97], v[100:103], off sc1
	s_cbranch_vccnz .LBB0_116
	v_mul_f32_e32 v92, 0xbfb8aa3b, v92
	v_mul_f32_e32 v88, 0xbfb8aa3b, v88
	v_mul_f32_e32 v93, 0xbfb8aa3b, v93
	v_mul_f32_e32 v89, 0xbfb8aa3b, v89
	v_mul_f32_e32 v94, 0xbfb8aa3b, v94
	v_mul_f32_e32 v90, 0xbfb8aa3b, v90
	v_mul_f32_e32 v95, 0xbfb8aa3b, v95
	v_mul_f32_e32 v91, 0xbfb8aa3b, v91
	v_exp_f32_e32 v92, v92
	v_exp_f32_e32 v88, v88
	v_exp_f32_e32 v93, v93
	v_exp_f32_e32 v89, v89
	v_exp_f32_e32 v94, v94
	v_exp_f32_e32 v90, v90
	v_exp_f32_e32 v95, v95
	v_exp_f32_e32 v91, v91
	v_add_f32_e32 v92, 1.0, v92
	v_add_f32_e32 v88, 1.0, v88
	v_add_f32_e32 v93, 1.0, v93
	v_add_f32_e32 v89, 1.0, v89
	v_add_f32_e32 v94, 1.0, v94
	v_add_f32_e32 v90, 1.0, v90
	v_add_f32_e32 v95, 1.0, v95
	v_add_f32_e32 v91, 1.0, v91
	v_rcp_f32_e32 v92, v92
	v_rcp_f32_e32 v88, v88
	v_rcp_f32_e32 v93, v93
	v_rcp_f32_e32 v89, v89
	v_rcp_f32_e32 v94, v94
	v_rcp_f32_e32 v90, v90
	v_rcp_f32_e32 v95, v95
	v_rcp_f32_e32 v91, v91
.LBB0_116:
	v_add_u32_e32 v96, 0x80, v165
	v_cvt_pk_bf16_f32 v92, v92, v93
	v_cvt_pk_bf16_f32 v93, v94, v95
	v_cvt_pk_bf16_f32 v94, v88, v89
	v_ashrrev_i32_e32 v88, 31, v96
	v_cvt_pk_bf16_f32 v95, v90, v91
	v_mul_lo_u32 v90, s82, v88
	v_mul_lo_u32 v91, s83, v96
	v_mad_u64_u32 v[88:89], s[90:91], s82, v96, 0
	v_add3_u32 v89, v89, v90, v91
	v_lshl_add_u64 v[88:89], v[88:89], 1, v[120:121]
	v_pk_add_f32 v[86:87], v[86:87], v[134:135]
	v_pk_add_f32 v[84:85], v[84:85], v[132:133]
	v_pk_add_f32 v[82:83], v[82:83], v[130:131]
	s_and_b64 vcc, exec, s[4:5]
	v_pk_add_f32 v[80:81], v[80:81], v[128:129]
	global_store_dwordx4 v[88:89], v[92:95], off sc1
	s_cbranch_vccnz .LBB0_118
	v_mul_f32_e32 v84, 0xbfb8aa3b, v84
	v_mul_f32_e32 v80, 0xbfb8aa3b, v80
	v_mul_f32_e32 v85, 0xbfb8aa3b, v85
	v_mul_f32_e32 v81, 0xbfb8aa3b, v81
	v_mul_f32_e32 v86, 0xbfb8aa3b, v86
	v_mul_f32_e32 v82, 0xbfb8aa3b, v82
	v_mul_f32_e32 v87, 0xbfb8aa3b, v87
	v_mul_f32_e32 v83, 0xbfb8aa3b, v83
	v_exp_f32_e32 v84, v84
	v_exp_f32_e32 v80, v80
	v_exp_f32_e32 v85, v85
	v_exp_f32_e32 v81, v81
	v_exp_f32_e32 v86, v86
	v_exp_f32_e32 v82, v82
	v_exp_f32_e32 v87, v87
	v_exp_f32_e32 v83, v83
	v_add_f32_e32 v84, 1.0, v84
	v_add_f32_e32 v80, 1.0, v80
	v_add_f32_e32 v85, 1.0, v85
	v_add_f32_e32 v81, 1.0, v81
	v_add_f32_e32 v86, 1.0, v86
	v_add_f32_e32 v82, 1.0, v82
	v_add_f32_e32 v87, 1.0, v87
	v_add_f32_e32 v83, 1.0, v83
	v_rcp_f32_e32 v84, v84
	v_rcp_f32_e32 v80, v80
	v_rcp_f32_e32 v85, v85
	v_rcp_f32_e32 v81, v81
	v_rcp_f32_e32 v86, v86
	v_rcp_f32_e32 v82, v82
	v_rcp_f32_e32 v87, v87
	v_rcp_f32_e32 v83, v83
.LBB0_118:
	v_cvt_pk_bf16_f32 v84, v84, v85
	v_cvt_pk_bf16_f32 v85, v86, v87
	v_cvt_pk_bf16_f32 v86, v80, v81
	v_add_u32_e32 v80, 0x90, v165
	v_ashrrev_i32_e32 v81, 31, v80
	v_cvt_pk_bf16_f32 v87, v82, v83
	v_mul_lo_u32 v82, s82, v81
	v_mul_lo_u32 v83, s83, v80
	v_mad_u64_u32 v[80:81], s[90:91], s82, v80, 0
	v_add3_u32 v81, v81, v82, v83
	v_lshl_add_u64 v[80:81], v[80:81], 1, v[120:121]
	v_pk_add_f32 v[78:79], v[78:79], v[134:135]
	v_pk_add_f32 v[76:77], v[76:77], v[132:133]
	v_pk_add_f32 v[74:75], v[74:75], v[130:131]
	s_and_b64 vcc, exec, s[4:5]
	v_pk_add_f32 v[72:73], v[72:73], v[128:129]
	global_store_dwordx4 v[80:81], v[84:87], off sc1
	s_cbranch_vccnz .LBB0_120
	v_mul_f32_e32 v76, 0xbfb8aa3b, v76
	v_mul_f32_e32 v72, 0xbfb8aa3b, v72
	v_mul_f32_e32 v77, 0xbfb8aa3b, v77
	v_mul_f32_e32 v73, 0xbfb8aa3b, v73
	v_mul_f32_e32 v78, 0xbfb8aa3b, v78
	v_mul_f32_e32 v74, 0xbfb8aa3b, v74
	v_mul_f32_e32 v79, 0xbfb8aa3b, v79
	v_mul_f32_e32 v75, 0xbfb8aa3b, v75
	v_exp_f32_e32 v76, v76
	v_exp_f32_e32 v72, v72
	v_exp_f32_e32 v77, v77
	v_exp_f32_e32 v73, v73
	v_exp_f32_e32 v78, v78
	v_exp_f32_e32 v74, v74
	v_exp_f32_e32 v79, v79
	v_exp_f32_e32 v75, v75
	v_add_f32_e32 v76, 1.0, v76
	v_add_f32_e32 v72, 1.0, v72
	v_add_f32_e32 v77, 1.0, v77
	v_add_f32_e32 v73, 1.0, v73
	v_add_f32_e32 v78, 1.0, v78
	v_add_f32_e32 v74, 1.0, v74
	v_add_f32_e32 v79, 1.0, v79
	v_add_f32_e32 v75, 1.0, v75
	v_rcp_f32_e32 v76, v76
	v_rcp_f32_e32 v72, v72
	v_rcp_f32_e32 v77, v77
	v_rcp_f32_e32 v73, v73
	v_rcp_f32_e32 v78, v78
	v_rcp_f32_e32 v74, v74
	v_rcp_f32_e32 v79, v79
	v_rcp_f32_e32 v75, v75
.LBB0_120:
	v_cvt_pk_bf16_f32 v76, v76, v77
	v_cvt_pk_bf16_f32 v77, v78, v79
	v_cvt_pk_bf16_f32 v78, v72, v73
	v_add_u32_e32 v72, 0xa0, v165
	v_ashrrev_i32_e32 v73, 31, v72
	v_cvt_pk_bf16_f32 v79, v74, v75
	v_mul_lo_u32 v74, s82, v73
	v_mul_lo_u32 v75, s83, v72
	v_mad_u64_u32 v[72:73], s[90:91], s82, v72, 0
	v_add3_u32 v73, v73, v74, v75
	v_lshl_add_u64 v[72:73], v[72:73], 1, v[120:121]
	v_pk_add_f32 v[70:71], v[70:71], v[134:135]
	v_pk_add_f32 v[68:69], v[68:69], v[132:133]
	v_pk_add_f32 v[66:67], v[66:67], v[130:131]
	s_and_b64 vcc, exec, s[4:5]
	v_pk_add_f32 v[64:65], v[64:65], v[128:129]
	global_store_dwordx4 v[72:73], v[76:79], off sc1
	s_cbranch_vccnz .LBB0_122
	v_mul_f32_e32 v68, 0xbfb8aa3b, v68
	v_mul_f32_e32 v64, 0xbfb8aa3b, v64
	v_mul_f32_e32 v69, 0xbfb8aa3b, v69
	v_mul_f32_e32 v65, 0xbfb8aa3b, v65
	v_mul_f32_e32 v70, 0xbfb8aa3b, v70
	v_mul_f32_e32 v66, 0xbfb8aa3b, v66
	v_mul_f32_e32 v71, 0xbfb8aa3b, v71
	v_mul_f32_e32 v67, 0xbfb8aa3b, v67
	v_exp_f32_e32 v68, v68
	v_exp_f32_e32 v64, v64
	v_exp_f32_e32 v69, v69
	v_exp_f32_e32 v65, v65
	v_exp_f32_e32 v70, v70
	v_exp_f32_e32 v66, v66
	v_exp_f32_e32 v71, v71
	v_exp_f32_e32 v67, v67
	v_add_f32_e32 v68, 1.0, v68
	v_add_f32_e32 v64, 1.0, v64
	v_add_f32_e32 v69, 1.0, v69
	v_add_f32_e32 v65, 1.0, v65
	v_add_f32_e32 v70, 1.0, v70
	v_add_f32_e32 v66, 1.0, v66
	v_add_f32_e32 v71, 1.0, v71
	v_add_f32_e32 v67, 1.0, v67
	v_rcp_f32_e32 v68, v68
	v_rcp_f32_e32 v64, v64
	v_rcp_f32_e32 v69, v69
	v_rcp_f32_e32 v65, v65
	v_rcp_f32_e32 v70, v70
	v_rcp_f32_e32 v66, v66
	v_rcp_f32_e32 v71, v71
	v_rcp_f32_e32 v67, v67
.LBB0_122:
	v_cvt_pk_bf16_f32 v68, v68, v69
	v_cvt_pk_bf16_f32 v69, v70, v71
	v_cvt_pk_bf16_f32 v70, v64, v65
	v_add_u32_e32 v64, 0xb0, v165
	v_ashrrev_i32_e32 v65, 31, v64
	v_cvt_pk_bf16_f32 v71, v66, v67
	v_mul_lo_u32 v66, s82, v65
	v_mul_lo_u32 v67, s83, v64
	v_mad_u64_u32 v[64:65], s[90:91], s82, v64, 0
	v_add3_u32 v65, v65, v66, v67
	v_lshl_add_u64 v[64:65], v[64:65], 1, v[120:121]
	global_store_dwordx4 v[64:65], v[68:71], off sc1
	s_xor_b64 s[88:89], s[88:89], -1
	s_andn2_b64 vcc, exec, s[88:89]
	s_cbranch_vccz .LBB0_125

; __device__ __forceinline__ unsigned cvt_pk_bf16(float lo, float hi) { unsigned r; asm volatile("v_cvt_pk_bf16_f32 %0, %1, %2" : "=v"(r) : "v"(lo), "v"(hi)); return r; }
; __device__ __forceinline__ float sigmoid_f(float x) { return __builtin_amdgcn_rcpf(1.0f + __builtin_amdgcn_exp2f(-1.4426950408889634f * x)); }
;     __device__ __forceinline__ void operator()(const f32x4 (&acc)[2][2][4][2], const Unit& u, int wr, int wc, int fr, int fq) const {
;     ...
;         const int row0 = u.pm * BM + wr * 64 + fr, c0 = wc * 32 + 8 * fq;
; #pragma unroll
;         for (int bj = 0; bj < 2; ++bj) {
;             const int c = c0 + bj * HALF;
;             if (mode == 2 && c >= 64) continue;
;             f32x4 b0 = (f32x4){0.f, 0.f, 0.f, 0.f}, b1 = b0;
;             if (mode == 1) { b0 = *(const f32x4*)(bgate + ct + c); b1 = *(const f32x4*)(bgate + ct + c + 4); }
; #pragma unroll
;             for (int ai = 0; ai < 2; ++ai)
; #pragma unroll
;                 for (int m = 0; m < 4; ++m) {
;                     f32x4 v0 = acc[ai][bj][m][0] + b0, v1 = acc[ai][bj][m][1] + b1;
;                     if (mode == 1) {
; #pragma unroll
;                         for (int e = 0; e < 4; ++e) { v0[e] = sigmoid_f(v0[e]); v1[e] = sigmoid_f(v1[e]); }
;                     }
;                     u32x4 w; w.x = cvt_pk_bf16(v0[0], v0[1]); w.y = cvt_pk_bf16(v0[2], v0[3]); w.z = cvt_pk_bf16(v1[0], v1[1]); w.w = cvt_pk_bf16(v1[2], v1[3]);
;                     *(u32x4*)(dst + (size_t)(row0 + ai * HALF + m * 16) * ldc + ct + c) = w;
;                 }
.LBB0_129:
	v_cvt_pk_bf16_f32 v60, v60, v61
	v_cvt_pk_bf16_f32 v61, v62, v63
	v_cvt_pk_bf16_f32 v62, v72, v73
	v_cvt_pk_bf16_f32 v63, v58, v59
	v_ashrrev_i32_e32 v58, 31, v165
	v_lshlrev_b32_e32 v144, 1, v146
	v_mul_lo_u32 v59, s83, v165
	v_mul_lo_u32 v58, s82, v58
	v_mad_u64_u32 v[72:73], s[84:85], s82, v165, 0
	v_lshl_add_u64 v[56:57], s[86:87], 0, v[144:145]
	v_add3_u32 v73, v73, v58, v59
	v_lshl_add_u64 v[72:73], v[72:73], 1, v[56:57]
	v_pk_add_f32 v[54:55], v[54:55], v[70:71]
	v_pk_add_f32 v[52:53], v[52:53], v[68:69]
	v_pk_add_f32 v[50:51], v[50:51], v[66:67]
	s_and_b64 vcc, exec, s[4:5]
	v_pk_add_f32 v[48:49], v[48:49], v[64:65]
	global_store_dwordx4 v[72:73], v[60:63], off offset:256 sc1
	s_cbranch_vccnz .LBB0_131
	v_mul_f32_e32 v52, 0xbfb8aa3b, v52
	v_mul_f32_e32 v48, 0xbfb8aa3b, v48
	v_mul_f32_e32 v53, 0xbfb8aa3b, v53
	v_mul_f32_e32 v49, 0xbfb8aa3b, v49
	v_mul_f32_e32 v54, 0xbfb8aa3b, v54
	v_mul_f32_e32 v50, 0xbfb8aa3b, v50
	v_mul_f32_e32 v55, 0xbfb8aa3b, v55
	v_mul_f32_e32 v51, 0xbfb8aa3b, v51
	v_exp_f32_e32 v52, v52
	v_exp_f32_e32 v48, v48
	v_exp_f32_e32 v53, v53
	v_exp_f32_e32 v49, v49
	v_exp_f32_e32 v54, v54
	v_exp_f32_e32 v50, v50
	v_exp_f32_e32 v55, v55
	v_exp_f32_e32 v51, v51
	v_add_f32_e32 v52, 1.0, v52
	v_add_f32_e32 v48, 1.0, v48
	v_add_f32_e32 v53, 1.0, v53
	v_add_f32_e32 v49, 1.0, v49
	v_add_f32_e32 v54, 1.0, v54
	v_add_f32_e32 v50, 1.0, v50
	v_add_f32_e32 v55, 1.0, v55
	v_add_f32_e32 v51, 1.0, v51
	v_rcp_f32_e32 v52, v52
	v_rcp_f32_e32 v48, v48
	v_rcp_f32_e32 v53, v53
	v_rcp_f32_e32 v49, v49
	v_rcp_f32_e32 v54, v54
	v_rcp_f32_e32 v50, v50
	v_rcp_f32_e32 v55, v55
	v_rcp_f32_e32 v51, v51
.LBB0_131:
	v_cvt_pk_bf16_f32 v52, v52, v53
	v_cvt_pk_bf16_f32 v53, v54, v55
	v_cvt_pk_bf16_f32 v54, v48, v49
	v_or_b32_e32 v48, 16, v165
	v_cvt_pk_bf16_f32 v55, v50, v51
	v_mul_lo_u32 v50, s83, v48
	v_mad_u64_u32 v[48:49], s[84:85], s82, v48, 0
	v_add3_u32 v49, v49, v58, v50
	v_lshl_add_u64 v[48:49], v[48:49], 1, v[56:57]
	v_pk_add_f32 v[46:47], v[46:47], v[70:71]
	v_pk_add_f32 v[44:45], v[44:45], v[68:69]
	v_pk_add_f32 v[42:43], v[42:43], v[66:67]
	s_and_b64 vcc, exec, s[4:5]
	v_pk_add_f32 v[40:41], v[40:41], v[64:65]
	global_store_dwordx4 v[48:49], v[52:55], off offset:256 sc1
	s_cbranch_vccnz .LBB0_133
	v_mul_f32_e32 v44, 0xbfb8aa3b, v44
	v_mul_f32_e32 v40, 0xbfb8aa3b, v40
	v_mul_f32_e32 v45, 0xbfb8aa3b, v45
	v_mul_f32_e32 v41, 0xbfb8aa3b, v41
	v_mul_f32_e32 v46, 0xbfb8aa3b, v46
	v_mul_f32_e32 v42, 0xbfb8aa3b, v42
	v_mul_f32_e32 v47, 0xbfb8aa3b, v47
	v_mul_f32_e32 v43, 0xbfb8aa3b, v43
	v_exp_f32_e32 v44, v44
	v_exp_f32_e32 v40, v40
	v_exp_f32_e32 v45, v45
	v_exp_f32_e32 v41, v41
	v_exp_f32_e32 v46, v46
	v_exp_f32_e32 v42, v42
	v_exp_f32_e32 v47, v47
	v_exp_f32_e32 v43, v43
	v_add_f32_e32 v44, 1.0, v44
	v_add_f32_e32 v40, 1.0, v40
	v_add_f32_e32 v45, 1.0, v45
	v_add_f32_e32 v41, 1.0, v41
	v_add_f32_e32 v46, 1.0, v46
	v_add_f32_e32 v42, 1.0, v42
	v_add_f32_e32 v47, 1.0, v47
	v_add_f32_e32 v43, 1.0, v43
	v_rcp_f32_e32 v44, v44
	v_rcp_f32_e32 v40, v40
	v_rcp_f32_e32 v45, v45
	v_rcp_f32_e32 v41, v41
	v_rcp_f32_e32 v46, v46
	v_rcp_f32_e32 v42, v42
	v_rcp_f32_e32 v47, v47
	v_rcp_f32_e32 v43, v43
.LBB0_133:
	v_cvt_pk_bf16_f32 v44, v44, v45
	v_cvt_pk_bf16_f32 v45, v46, v47
	v_cvt_pk_bf16_f32 v46, v40, v41
	v_or_b32_e32 v40, 32, v165
	v_cvt_pk_bf16_f32 v47, v42, v43
	v_mul_lo_u32 v42, s83, v40
	v_mad_u64_u32 v[40:41], s[84:85], s82, v40, 0
	v_add3_u32 v41, v41, v58, v42
	v_lshl_add_u64 v[40:41], v[40:41], 1, v[56:57]
	v_pk_add_f32 v[38:39], v[38:39], v[70:71]
	v_pk_add_f32 v[36:37], v[36:37], v[68:69]
	v_pk_add_f32 v[34:35], v[34:35], v[66:67]
	s_and_b64 vcc, exec, s[4:5]
	v_pk_add_f32 v[32:33], v[32:33], v[64:65]
	global_store_dwordx4 v[40:41], v[44:47], off offset:256 sc1
	s_cbranch_vccnz .LBB0_135
	v_mul_f32_e32 v36, 0xbfb8aa3b, v36
	v_mul_f32_e32 v32, 0xbfb8aa3b, v32
	v_mul_f32_e32 v37, 0xbfb8aa3b, v37
	v_mul_f32_e32 v33, 0xbfb8aa3b, v33
	v_mul_f32_e32 v38, 0xbfb8aa3b, v38
	v_mul_f32_e32 v34, 0xbfb8aa3b, v34
	v_mul_f32_e32 v39, 0xbfb8aa3b, v39
	v_mul_f32_e32 v35, 0xbfb8aa3b, v35
	v_exp_f32_e32 v36, v36
	v_exp_f32_e32 v32, v32
	v_exp_f32_e32 v37, v37
	v_exp_f32_e32 v33, v33
	v_exp_f32_e32 v38, v38
	v_exp_f32_e32 v34, v34
	v_exp_f32_e32 v39, v39
	v_exp_f32_e32 v35, v35
	v_add_f32_e32 v36, 1.0, v36
	v_add_f32_e32 v32, 1.0, v32
	v_add_f32_e32 v37, 1.0, v37
	v_add_f32_e32 v33, 1.0, v33
	v_add_f32_e32 v38, 1.0, v38
	v_add_f32_e32 v34, 1.0, v34
	v_add_f32_e32 v39, 1.0, v39
	v_add_f32_e32 v35, 1.0, v35
	v_rcp_f32_e32 v36, v36
	v_rcp_f32_e32 v32, v32
	v_rcp_f32_e32 v37, v37
	v_rcp_f32_e32 v33, v33
	v_rcp_f32_e32 v38, v38
	v_rcp_f32_e32 v34, v34
	v_rcp_f32_e32 v39, v39
	v_rcp_f32_e32 v35, v35
.LBB0_135:
	v_cvt_pk_bf16_f32 v36, v36, v37
	v_cvt_pk_bf16_f32 v37, v38, v39
	v_cvt_pk_bf16_f32 v38, v32, v33
	v_or_b32_e32 v32, 48, v165
	v_cvt_pk_bf16_f32 v39, v34, v35
	v_mul_lo_u32 v34, s83, v32
	v_mad_u64_u32 v[32:33], s[84:85], s82, v32, 0
	v_add3_u32 v33, v33, v58, v34
	v_lshl_add_u64 v[32:33], v[32:33], 1, v[56:57]
	v_pk_add_f32 v[30:31], v[30:31], v[70:71]
	v_pk_add_f32 v[28:29], v[28:29], v[68:69]
	v_pk_add_f32 v[26:27], v[26:27], v[66:67]
	s_and_b64 vcc, exec, s[4:5]
	v_pk_add_f32 v[24:25], v[24:25], v[64:65]
	global_store_dwordx4 v[32:33], v[36:39], off offset:256 sc1
	s_cbranch_vccnz .LBB0_137
	v_mul_f32_e32 v28, 0xbfb8aa3b, v28
	v_mul_f32_e32 v24, 0xbfb8aa3b, v24
	v_mul_f32_e32 v29, 0xbfb8aa3b, v29
	v_mul_f32_e32 v25, 0xbfb8aa3b, v25
	v_mul_f32_e32 v30, 0xbfb8aa3b, v30
	v_mul_f32_e32 v26, 0xbfb8aa3b, v26
	v_mul_f32_e32 v31, 0xbfb8aa3b, v31
	v_mul_f32_e32 v27, 0xbfb8aa3b, v27
	v_exp_f32_e32 v28, v28
	v_exp_f32_e32 v24, v24
	v_exp_f32_e32 v29, v29
	v_exp_f32_e32 v25, v25
	v_exp_f32_e32 v30, v30
	v_exp_f32_e32 v26, v26
	v_exp_f32_e32 v31, v31
	v_exp_f32_e32 v27, v27
	v_add_f32_e32 v28, 1.0, v28
	v_add_f32_e32 v24, 1.0, v24
	v_add_f32_e32 v29, 1.0, v29
	v_add_f32_e32 v25, 1.0, v25
	v_add_f32_e32 v30, 1.0, v30
	v_add_f32_e32 v26, 1.0, v26
	v_add_f32_e32 v31, 1.0, v31
	v_add_f32_e32 v27, 1.0, v27
	v_rcp_f32_e32 v28, v28
	v_rcp_f32_e32 v24, v24
	v_rcp_f32_e32 v29, v29
	v_rcp_f32_e32 v25, v25
	v_rcp_f32_e32 v30, v30
	v_rcp_f32_e32 v26, v26
	v_rcp_f32_e32 v31, v31
	v_rcp_f32_e32 v27, v27
; __device__ __forceinline__ unsigned cvt_pk_bf16(float lo, float hi) { unsigned r; asm volatile("v_cvt_pk_bf16_f32 %0, %1, %2" : "=v"(r) : "v"(lo), "v"(hi)); return r; }
; __device__ __forceinline__ float sigmoid_f(float x) { return __builtin_amdgcn_rcpf(1.0f + __builtin_amdgcn_exp2f(-1.4426950408889634f * x)); }
; #define PG8_BAR __builtin_amdgcn_s_barrier()
;     __device__ __forceinline__ void operator()(const f32x4 (&acc)[2][2][4][2], const Unit& u, int wr, int wc, int fr, int fq) const {
;     ...
;         const int row0 = u.pm * BM + wr * 64 + fr, c0 = wc * 32 + 8 * fq;
; #pragma unroll
;         for (int bj = 0; bj < 2; ++bj) {
;             const int c = c0 + bj * HALF;
;             if (mode == 2 && c >= 64) continue;
;             f32x4 b0 = (f32x4){0.f, 0.f, 0.f, 0.f}, b1 = b0;
;             if (mode == 1) { b0 = *(const f32x4*)(bgate + ct + c); b1 = *(const f32x4*)(bgate + ct + c + 4); }
; #pragma unroll
;             for (int ai = 0; ai < 2; ++ai)
; #pragma unroll
;                 for (int m = 0; m < 4; ++m) {
;                     f32x4 v0 = acc[ai][bj][m][0] + b0, v1 = acc[ai][bj][m][1] + b1;
;                     if (mode == 1) {
; #pragma unroll
;                         for (int e = 0; e < 4; ++e) { v0[e] = sigmoid_f(v0[e]); v1[e] = sigmoid_f(v1[e]); }
;                     }
;                     u32x4 w; w.x = cvt_pk_bf16(v0[0], v0[1]); w.y = cvt_pk_bf16(v0[2], v0[3]); w.z = cvt_pk_bf16(v1[0], v1[1]); w.w = cvt_pk_bf16(v1[2], v1[3]);
;                     *(u32x4*)(dst + (size_t)(row0 + ai * HALF + m * 16) * ldc + ct + c) = w;
;                 }
; template <class Epi, class Sched, bool ALIGN_EPI = false, bool SP2 = false>
; __device__ __forceinline__ void gemm_phase(PG8_LAS unsigned char* lds, const Gemm g, const Sched& S, const Epi& E) {
;     ...
;         }
;         if constexpr (ALIGN_EPI) { if (wr == 0) PG8_BAR; }
;         if constexpr (!Epi::AFTER_DRAIN) { E(acc, cur, wr, wc, fr, fq); S.done(cur); }
;         if (!has_next) break;
.LBB0_137:
	v_add_u32_e32 v32, 0x80, v165
	v_cvt_pk_bf16_f32 v28, v28, v29
	v_cvt_pk_bf16_f32 v29, v30, v31
	v_cvt_pk_bf16_f32 v30, v24, v25
	v_ashrrev_i32_e32 v24, 31, v32
	v_cvt_pk_bf16_f32 v31, v26, v27
	v_mul_lo_u32 v26, s82, v24
	v_mul_lo_u32 v27, s83, v32
	v_mad_u64_u32 v[24:25], s[84:85], s82, v32, 0
	v_add3_u32 v25, v25, v26, v27
	v_lshl_add_u64 v[24:25], v[24:25], 1, v[56:57]
	v_pk_add_f32 v[22:23], v[22:23], v[70:71]
	v_pk_add_f32 v[20:21], v[20:21], v[68:69]
	v_pk_add_f32 v[18:19], v[18:19], v[66:67]
	s_and_b64 vcc, exec, s[4:5]
	v_pk_add_f32 v[16:17], v[16:17], v[64:65]
	global_store_dwordx4 v[24:25], v[28:31], off offset:256 sc1
	s_cbranch_vccnz .LBB0_139
	v_mul_f32_e32 v20, 0xbfb8aa3b, v20
	v_mul_f32_e32 v16, 0xbfb8aa3b, v16
	v_mul_f32_e32 v21, 0xbfb8aa3b, v21
	v_mul_f32_e32 v17, 0xbfb8aa3b, v17
	v_mul_f32_e32 v22, 0xbfb8aa3b, v22
	v_mul_f32_e32 v18, 0xbfb8aa3b, v18
	v_mul_f32_e32 v23, 0xbfb8aa3b, v23
	v_mul_f32_e32 v19, 0xbfb8aa3b, v19
	v_exp_f32_e32 v20, v20
	v_exp_f32_e32 v16, v16
	v_exp_f32_e32 v21, v21
	v_exp_f32_e32 v17, v17
	v_exp_f32_e32 v22, v22
	v_exp_f32_e32 v18, v18
	v_exp_f32_e32 v23, v23
	v_exp_f32_e32 v19, v19
	v_add_f32_e32 v20, 1.0, v20
	v_add_f32_e32 v16, 1.0, v16
	v_add_f32_e32 v21, 1.0, v21
	v_add_f32_e32 v17, 1.0, v17
	v_add_f32_e32 v22, 1.0, v22
	v_add_f32_e32 v18, 1.0, v18
	v_add_f32_e32 v23, 1.0, v23
	v_add_f32_e32 v19, 1.0, v19
	v_rcp_f32_e32 v20, v20
	v_rcp_f32_e32 v16, v16
	v_rcp_f32_e32 v21, v21
	v_rcp_f32_e32 v17, v17
	v_rcp_f32_e32 v22, v22
	v_rcp_f32_e32 v18, v18
	v_rcp_f32_e32 v23, v23
	v_rcp_f32_e32 v19, v19
.LBB0_139:
	v_cvt_pk_bf16_f32 v20, v20, v21
	v_cvt_pk_bf16_f32 v21, v22, v23
	v_cvt_pk_bf16_f32 v22, v16, v17
	v_add_u32_e32 v16, 0x90, v165
	v_ashrrev_i32_e32 v17, 31, v16
	v_cvt_pk_bf16_f32 v23, v18, v19
	v_mul_lo_u32 v18, s82, v17
	v_mul_lo_u32 v19, s83, v16
	v_mad_u64_u32 v[16:17], s[84:85], s82, v16, 0
	v_add3_u32 v17, v17, v18, v19
	v_lshl_add_u64 v[16:17], v[16:17], 1, v[56:57]
	v_pk_add_f32 v[14:15], v[14:15], v[70:71]
	v_pk_add_f32 v[12:13], v[12:13], v[68:69]
	v_pk_add_f32 v[10:11], v[10:11], v[66:67]
	s_and_b64 vcc, exec, s[4:5]
	v_pk_add_f32 v[8:9], v[8:9], v[64:65]
	global_store_dwordx4 v[16:17], v[20:23], off offset:256 sc1
	s_cbranch_vccnz .LBB0_141
	v_mul_f32_e32 v12, 0xbfb8aa3b, v12
	v_mul_f32_e32 v8, 0xbfb8aa3b, v8
	v_mul_f32_e32 v13, 0xbfb8aa3b, v13
	v_mul_f32_e32 v9, 0xbfb8aa3b, v9
	v_mul_f32_e32 v14, 0xbfb8aa3b, v14
	v_mul_f32_e32 v10, 0xbfb8aa3b, v10
	v_mul_f32_e32 v15, 0xbfb8aa3b, v15
	v_mul_f32_e32 v11, 0xbfb8aa3b, v11
	v_exp_f32_e32 v12, v12
	v_exp_f32_e32 v8, v8
	v_exp_f32_e32 v13, v13
	v_exp_f32_e32 v9, v9
	v_exp_f32_e32 v14, v14
	v_exp_f32_e32 v10, v10
	v_exp_f32_e32 v15, v15
	v_exp_f32_e32 v11, v11
	v_add_f32_e32 v12, 1.0, v12
	v_add_f32_e32 v8, 1.0, v8
	v_add_f32_e32 v13, 1.0, v13
	v_add_f32_e32 v9, 1.0, v9
	v_add_f32_e32 v14, 1.0, v14
	v_add_f32_e32 v10, 1.0, v10
	v_add_f32_e32 v15, 1.0, v15
	v_add_f32_e32 v11, 1.0, v11
	v_rcp_f32_e32 v12, v12
	v_rcp_f32_e32 v8, v8
	v_rcp_f32_e32 v13, v13
	v_rcp_f32_e32 v9, v9
	v_rcp_f32_e32 v14, v14
	v_rcp_f32_e32 v10, v10
	v_rcp_f32_e32 v15, v15
	v_rcp_f32_e32 v11, v11
.LBB0_141:
	v_cvt_pk_bf16_f32 v12, v12, v13
	v_cvt_pk_bf16_f32 v13, v14, v15
	v_cvt_pk_bf16_f32 v14, v8, v9
	v_add_u32_e32 v8, 0xa0, v165
	v_ashrrev_i32_e32 v9, 31, v8
	v_cvt_pk_bf16_f32 v15, v10, v11
	v_mul_lo_u32 v10, s82, v9
	v_mul_lo_u32 v11, s83, v8
	v_mad_u64_u32 v[8:9], s[84:85], s82, v8, 0
	v_add3_u32 v9, v9, v10, v11
	v_lshl_add_u64 v[8:9], v[8:9], 1, v[56:57]
	v_pk_add_f32 v[6:7], v[6:7], v[70:71]
	v_pk_add_f32 v[4:5], v[4:5], v[68:69]
	v_pk_add_f32 v[2:3], v[2:3], v[66:67]
	s_and_b64 vcc, exec, s[4:5]
	v_pk_add_f32 v[0:1], v[0:1], v[64:65]
	global_store_dwordx4 v[8:9], v[12:15], off offset:256 sc1
	s_cbranch_vccnz .LBB0_143
	v_mul_f32_e32 v4, 0xbfb8aa3b, v4
	v_mul_f32_e32 v0, 0xbfb8aa3b, v0
	v_mul_f32_e32 v5, 0xbfb8aa3b, v5
	v_mul_f32_e32 v1, 0xbfb8aa3b, v1
	v_mul_f32_e32 v6, 0xbfb8aa3b, v6
	v_mul_f32_e32 v2, 0xbfb8aa3b, v2
	v_mul_f32_e32 v7, 0xbfb8aa3b, v7
	v_mul_f32_e32 v3, 0xbfb8aa3b, v3
	v_exp_f32_e32 v4, v4
	v_exp_f32_e32 v0, v0
	v_exp_f32_e32 v5, v5
	v_exp_f32_e32 v1, v1
	v_exp_f32_e32 v6, v6
	v_exp_f32_e32 v2, v2
	v_exp_f32_e32 v7, v7
	v_exp_f32_e32 v3, v3
	v_add_f32_e32 v4, 1.0, v4
	v_add_f32_e32 v0, 1.0, v0
	v_add_f32_e32 v5, 1.0, v5
	v_add_f32_e32 v1, 1.0, v1
	v_add_f32_e32 v6, 1.0, v6
	v_add_f32_e32 v2, 1.0, v2
	v_add_f32_e32 v7, 1.0, v7
	v_add_f32_e32 v3, 1.0, v3
	v_rcp_f32_e32 v4, v4
	v_rcp_f32_e32 v0, v0
	v_rcp_f32_e32 v5, v5
	v_rcp_f32_e32 v1, v1
	v_rcp_f32_e32 v6, v6
	v_rcp_f32_e32 v2, v2
	v_rcp_f32_e32 v7, v7
	v_rcp_f32_e32 v3, v3
.LBB0_143:
	v_cvt_pk_bf16_f32 v4, v4, v5
	v_cvt_pk_bf16_f32 v5, v6, v7
	v_cvt_pk_bf16_f32 v6, v0, v1
	v_add_u32_e32 v0, 0xb0, v165
	v_ashrrev_i32_e32 v1, 31, v0
	v_cvt_pk_bf16_f32 v7, v2, v3
	v_mul_lo_u32 v2, s82, v1
	v_mul_lo_u32 v3, s83, v0
	v_mad_u64_u32 v[0:1], s[4:5], s82, v0, 0
	v_add3_u32 v1, v1, v2, v3
	v_lshl_add_u64 v[0:1], v[0:1], 1, v[56:57]
	global_store_dwordx4 v[0:1], v[4:7], off offset:256 sc1
	s_andn2_b64 vcc, exec, s[0:1]
	s_mov_b64 s[0:1], -1
	s_cbranch_vccnz .LBB0_83
.LBB0_144:
	s_cmp_eq_u32 s68, 3
	s_cbranch_scc0 .Lp1_a_skip
	s_waitcnt vmcnt(0)
	s_barrier
	v_readfirstlane_b32 s100, v226
	s_nop 0
	s_cmp_lg_u32 s100, 0
	s_cbranch_scc1 .Lp1_a_skip
	s_mov_b32 s100, 1
	s_nop 0
	v_writelane_b32 v255, s100, 6
	s_mov_b64 s[100:101], exec
	s_mov_b64 exec, 1
	v_mov_b32_e32 v0, 0x8000
	v_mov_b32_e32 v1, 1
	global_atomic_add v0, v1, s[30:31]
	s_mov_b64 exec, s[100:101]

; __global__ void __launch_bounds__(NWAVES * 64, 2) fwd_kernel(Args a) {
;     ...
;             constexpr int NUNITS = (MTOK / 256) * (INWP / 256), NDEF = I_IN + I_WC + I_QB + I_KVB + 2 * I_SQ;
;             const int iL = (NUNITS - 1) / G, nlast = NUNITS - iL * G, idle = G - nlast;
;             const int npart = idle > 0 ? idle : G, rank = idle > 0 ? bx - nlast : bx;
;             if (rank >= 0) {
.LBB0_148:
	s_add_u32 s16, s30, 0x200000
	s_addc_u32 s17, s31, 0
	s_add_u32 s22, s30, 0xc00000
	s_addc_u32 s23, s31, 0
	s_add_u32 s78, s30, 0x1000000
	s_addc_u32 s79, s31, 0
	s_add_u32 s76, s30, 0x1800000
	v_readlane_b32 s86, v254, 11
	s_addc_u32 s77, s31, 0
	s_abs_i32 s88, s86
	v_cvt_f32_u32_e32 v0, s88
	s_sub_i32 s0, 0, s88
	v_mov_b32_e32 v64, v226
	v_readlane_b32 s87, v254, 12
	v_rcp_iflag_f32_e32 v0, v0
	s_nop 0
	v_mul_f32_e32 v0, 0x4f7ffffe, v0
	v_cvt_u32_f32_e32 v0, v0
	s_nop 0
	v_readfirstlane_b32 s1, v0
	s_mul_i32 s0, s0, s1
	s_mul_hi_u32 s0, s1, s0
	s_add_i32 s89, s1, s0
	s_mul_hi_u32 s0, s89, 0x43f
	s_mul_i32 s0, s0, s88
	s_sub_i32 s0, 0x43f, s0
	s_sub_i32 s1, s0, s88
	s_cmp_ge_u32 s0, s88
	s_cselect_b32 s0, s1, s0
	s_sub_i32 s1, s0, s88
	s_cmp_ge_u32 s0, s88
	s_cselect_b32 s0, s1, s0
	s_add_i32 s3, s0, 1
	s_sub_i32 s25, s86, s3
	s_cmp_gt_i32 s25, 0
	s_cselect_b64 s[4:5], -1, 0
	s_and_b64 s[0:1], s[4:5], exec
	s_cselect_b32 s0, s3, 0
	s_sub_i32 s0, s2, s0
	v_writelane_b32 v255, s0, 2
	v_writelane_b32 v255, s25, 3
	s_cmp_lt_i32 s0, 0
	v_readfirstlane_b32 s1, v64
	s_cbranch_scc1 .LBB0_211
	s_ashr_i32 s34, s1, 6
	s_lshl_b32 s0, s0, 3
	s_add_i32 s35, s34, s0
	s_add_i32 s33, s35, 0x10a0
	s_cmpk_gt_i32 s33, 0x1edf
	s_cbranch_scc1 .LBB0_211
	s_cmpk_gt_i32 s33, 0x109f
	s_cbranch_scc0 .LBB0_155
	s_cmpk_gt_u32 s33, 0x129f
	s_cbranch_scc0 .LBB0_156
	s_cmpk_gt_u32 s33, 0x14df
	s_cbranch_scc0 .LBB0_157
	s_cmpk_gt_u32 s33, 0x16df
	s_cbranch_scc0 .LBB0_158
	s_cmpk_gt_u32 s33, 0x1adf
	s_cselect_b64 s[0:1], -1, 0
	s_and_b64 s[0:1], s[0:1], exec
	s_movk_i32 s3, 0xe520
	s_cselect_b32 s3, s3, 0xffffe920
	s_cselect_b32 s1, s77, s79
	s_cselect_b32 s0, s76, s78
	s_cselect_b32 s7, s49, s47
	s_cselect_b32 s6, s48, s46
	s_add_i32 s3, s3, s33
	s_lshl_b32 s8, s33, 6
	s_lshr_b32 s3, s3, 5
	s_and_b32 s13, s8, 0x7c0
	s_mov_b64 s[8:9], 0
	s_branch .LBB0_159

; #define PHASE_IDS() int tid_ = threadIdx.x; asm volatile("" : "+v"(tid_)); const int tid = tid_, lane = tid & 63, wave = __builtin_amdgcn_readfirstlane(tid >> 6), gw = vcu * NWAVES + wave; \
;     LAS float* scr = (LAS float*)(ldsl + wave * TSCR_BYTES); (void)scr; (void)gw; (void)lane; (void)tid
; __global__ void __launch_bounds__(NWAVES * 64, 2) fwd_kernel(Args a) {
;     ...
;     xcd_barrier(bar);
;     {
;         PHASE_IDS();
;         const float* cw = a.in[5]; const float* qg = a.in[7]; const float* kvg = a.in[9];
;         const float gkr = a.in[12][128 + lane], ifq = INV_FREQ[lane & 31];
;         for (int m = gw; m < MTOK; m += NGW) {
;             const int t = m & (SEQL - 1);
;             const bf16* zr = zconv + (size_t)m * 3072;
; #pragma unroll
;             for (int ch = 0; ch < 2; ++ch) {
;                 const int c = ch * 512 + lane * 8;
;                 const v4u z4 = {0u, 0u, 0u, 0u};
;                 const v4u zb = *(const v4u*)(zr + c), zc0 = *(const v4u*)(zr + 1024 + c), zv0 = *(const v4u*)(zr + 2048 + c);
;                 const v4u zc1 = t >= 1 ? *(const v4u*)(zr - 3072 + 1024 + c) : z4, zv1 = t >= 1 ? *(const v4u*)(zr - 3072 + 2048 + c) : z4;
;                 const v4u zc2 = t >= 2 ? *(const v4u*)(zr - 6144 + 1024 + c) : z4, zv2 = t >= 2 ? *(const v4u*)(zr - 6144 + 2048 + c) : z4;
.LBB0_211:
	s_waitcnt vmcnt(0)
	s_waitcnt lgkmcnt(0)
	s_barrier
	v_readfirstlane_b32 s100, v226
	s_nop 0
	s_cmp_lg_u32 s100, 0
	s_cbranch_scc1 .Lp1_w_done
	s_mov_b64 s[100:101], exec
	s_mov_b64 exec, 1
	v_mov_b32_e32 v0, 0x8000
	v_readlane_b32 s0, v255, 6
	s_nop 1
	s_cmp_lg_u32 s0, 0
	s_cbranch_scc1 .Lp1_w_poll0
	v_mov_b32_e32 v1, 1
	global_atomic_add v0, v1, s[30:31]
.Lp1_w_poll0:
	v_readlane_b32 s1, v254, 11
	s_mov_b32 s0, 0
.Lp1_w_poll:
	global_load_dword v1, v0, s[30:31] sc1
	s_waitcnt vmcnt(0)
	v_readfirstlane_b32 s3, v1
	s_nop 1
	s_cmp_ge_u32 s3, s1
	s_cbranch_scc1 .Lp1_w_got
	s_sleep 2
	s_add_u32 s0, s0, 1
	s_cmp_lt_u32 s0, 0x100000
	s_cbranch_scc1 .Lp1_w_poll
.Lp1_w_got:
	buffer_inv sc1
	s_waitcnt vmcnt(0)
	s_mov_b64 exec, s[100:101]
.Lp1_w_done:
	s_barrier
	v_writelane_b32 v255, s12, 4
	v_writelane_b32 v255, s90, 5
	s_nop 1
	v_readlane_b32 s0, v255, 2
	v_readlane_b32 s1, v255, 3
	v_readlane_b32 s3, v254, 11
	s_nop 1
	s_cmp_gt_i32 s1, 0
	s_cselect_b32 s12, s1, s3
	s_lshl_b32 s12, s12, 3
	s_lshl_b32 s90, s0, 3
	s_cmp_lt_i32 s0, 0
	s_cselect_b32 s90, 0x4000, s90
	v_mov_b32_e32 v0, v226
	s_nop 0
	v_readfirstlane_b32 s0, v0
	s_ashr_i32 s4, s0, 6
	s_add_i32 s3, s4, s90
	s_cmpk_gt_i32 s3, 0x1fff
	s_cbranch_scc1 .LBB0_285
	v_and_b32_e32 v4, 63, v0
	v_and_b32_e32 v0, 31, v0
	v_lshlrev_b32_e32 v0, 2, v0
	s_getpc_b64 s[0:1]
	s_add_u32 s0, s0, _ZL8INV_FREQ@rel32@lo+4
	s_addc_u32 s1, s1, _ZL8INV_FREQ@rel32@hi+12
	v_lshlrev_b32_e32 v30, 2, v4
	global_load_dword v66, v0, s[0:1]
	global_load_dword v67, v30, s[44:45] offset:512
	s_add_u32 s6, s62, 0x1000
	s_addc_u32 s7, s63, 0
	s_add_u32 s20, s62, 0x2000
	v_mov_b32_e32 v31, 0
	s_addc_u32 s21, s63, 0
	v_lshlrev_b32_e32 v0, 5, v4
	v_mov_b32_e32 v1, v31
	v_lshl_add_u64 v[32:33], s[66:67], 0, v[0:1]
	v_lshl_add_u64 v[36:37], s[38:39], 0, v[0:1]
	v_lshl_add_u64 v[38:39], s[62:63], 0, v[0:1]
	v_lshl_add_u64 v[40:41], s[6:7], 0, v[0:1]
	v_lshl_add_u64 v[42:43], s[20:21], 0, v[0:1]
	v_or_b32_e32 v0, 0x800, v0
	v_lshl_add_u64 v[44:45], s[6:7], 0, v[0:1]
	s_ashr_i32 s5, s4, 31
	s_ashr_i32 s6, s90, 31
	s_add_u32 s4, s4, s90
	s_addc_u32 s5, s5, s6
	s_lshl_b64 s[6:7], s[4:5], 2
	v_lshl_add_u64 v[46:47], s[20:21], 0, v[0:1]
	s_add_u32 s20, s54, s6
	s_addc_u32 s21, s55, s7
	s_ashr_i32 s13, s12, 31
	s_lshl_b64 s[26:27], s[12:13], 2
	s_add_u32 s24, s6, 0x15a00000
	v_lshlrev_b32_e32 v2, 4, v4
	s_addc_u32 s25, s7, 0
	s_lshl_b64 s[6:7], s[4:5], 11
	v_or_b32_e32 v48, s6, v2
	v_mov_b32_e32 v49, s7
	s_lshl_b64 s[6:7], s[4:5], 10
	v_or_b32_e32 v50, s6, v2
	v_mov_b32_e32 v51, s7
	s_lshl_b64 s[6:7], s[4:5], 7
	v_lshl_or_b32 v0, v4, 1, s6
	v_mov_b32_e32 v1, s7
	s_mov_b64 s[34:35], 0x100000
	v_lshl_add_u64 v[52:53], v[0:1], 0, s[34:35]
	s_lshl_b64 s[34:35], s[4:5], 8
	v_or_b32_e32 v0, s34, v30
	v_mov_b32_e32 v1, s35
	s_mov_b64 s[34:35], 0x15800000
	v_mov_b32_e32 v3, v31
	s_lshl_b64 s[36:37], s[12:13], 11
	s_lshl_b64 s[38:39], s[12:13], 10
	s_lshl_b64 s[40:41], s[12:13], 7
	v_lshl_add_u64 v[54:55], v[0:1], 0, s[34:35]
	s_lshl_b64 s[46:47], s[12:13], 8
	v_lshl_add_u64 v[56:57], s[6:7], 0, v[30:31]
	s_mul_i32 s13, s5, 0x600
	s_mul_hi_u32 s6, s4, 0x600
	v_mov_b32_e32 v0, 0x600
	s_add_i32 s33, s6, s13
	v_mad_u64_u32 v[58:59], s[6:7], s4, v0, v[2:3]
	s_mulk_i32 s5, 0x1800
	s_mul_hi_u32 s6, s4, 0x1800
	s_mul_i32 s34, s4, 0x600
	s_add_i32 s6, s6, s5
	s_mulk_i32 s4, 0x1800
	s_mov_b32 s56, 0x6dc9c883
	v_lshl_add_u64 v[34:35], s[66:67], 0, v[2:3]
	v_cmp_gt_u32_e64 s[0:1], 32, v4
	v_cmp_eq_u32_e64 s[8:9], 0, v4
	v_add_u32_e32 v59, s13, v59
	s_mul_hi_i32 s49, s12, 0x600
	s_mul_i32 s48, s12, 0x600
	v_lshl_or_b32 v60, v4, 3, s34
	v_mov_b32_e32 v61, s33
	v_or_b32_e32 v62, s4, v2
	v_mov_b32_e32 v63, s6
	s_mul_hi_i32 s55, s12, 0x1800
	s_mul_i32 s54, s12, 0x1800
	s_brev_b32 s13, 64
	s_mov_b32 s33, 0x9200000
	v_mbcnt_hi_u32_b32 v30, -1, v147
	v_mov_b32_e32 v68, 0x358637bd
	s_mov_b32 s34, 0x800000
	s_mov_b32 s35, 0x3000000
	s_mov_b32 s57, 0x3fc45f30
	s_mov_b32 s60, 0x3c00000
	s_branch .LBB0_264

; __device__ __forceinline__ unsigned xb_add(unsigned* p, unsigned v) { return __hip_atomic_fetch_add(p, v, __ATOMIC_RELAXED, __HIP_MEMORY_SCOPE_AGENT); }
; __device__ __forceinline__ void xcd_barrier(const XcdBarrier& b) {
;     asm volatile("s_waitcnt vmcnt(0)" ::: "memory");
;     __syncthreads();
;     if (threadIdx.x == 0) {
;         unsigned* bar = b.bar;
;         __builtin_amdgcn_s_waitcnt(0);
;         unsigned nloc = b.st[0], nx = b.st[1];
;         if (nloc == 0u) { xcd_barrier_complete(bar, b.x, nloc, nx); b.st[0] = nloc; b.st[1] = nx; }
;         const unsigned old = xb_add(&bar[XB_XSUB(b.x)], 1u);
.LBB0_285:
	v_readlane_b32 s12, v255, 4
	v_readlane_b32 s90, v255, 5
	s_add_u32 s14, s30, 0x2000000
	s_addc_u32 s15, s31, 0
	s_nop 1
	s_waitcnt vmcnt(0)
	s_barrier
	s_mov_b64 s[0:1], exec
	v_readlane_b32 s4, v254, 9
	v_readlane_b32 s5, v254, 10
	s_and_b64 s[4:5], s[0:1], s[4:5]
	s_mov_b64 exec, s[4:5]
	s_cbranch_execz .LBB0_335
	s_add_i32 s3, 0, 0x23fc0
	v_mov_b32_e32 v0, s3
	s_waitcnt vmcnt(0) expcnt(0) lgkmcnt(0)
	buffer_inv sc1
	ds_read_b32 v2, v0
	s_add_i32 s3, 0, 0x23fc4
	v_mov_b32_e32 v0, s3
	ds_read_b32 v0, v0
	s_waitcnt lgkmcnt(1)
	v_cmp_ne_u32_e32 vcc, 0, v2
	s_cbranch_vccnz .LBB0_301
	s_add_u32 s4, s30, 0x1000
	s_addc_u32 s5, s31, 0
	s_add_u32 s6, s30, 0x1100
	s_addc_u32 s7, s31, 0
	s_add_u32 s8, s30, 0x1200
	v_readlane_b32 s3, v254, 8
	s_addc_u32 s9, s31, 0
	s_mul_i32 s3, s87, s3
	s_add_u32 s20, s30, 0x1300
	s_mul_i32 s3, s3, s86
	s_addc_u32 s21, s31, 0
	s_mov_b32 s13, 1
	v_mov_b32_e32 v16, 0
	s_branch .LBB0_289

; __global__ void __launch_bounds__(NWAVES * 64, 2) fwd_kernel(Args a) {
	.amdhsa_kernel _Z10fwd_kernel4Args
		.amdhsa_group_segment_fixed_size 0
		.amdhsa_private_segment_fixed_size 0
		.amdhsa_kernarg_size 432
		.amdhsa_user_sgpr_count 2
		.amdhsa_user_sgpr_dispatch_ptr 0
		.amdhsa_user_sgpr_queue_ptr 0
		.amdhsa_user_sgpr_kernarg_segment_ptr 1
		.amdhsa_user_sgpr_dispatch_id 0
		.amdhsa_user_sgpr_kernarg_preload_length 0
		.amdhsa_user_sgpr_kernarg_preload_offset 0
		.amdhsa_user_sgpr_private_segment_size 0
		.amdhsa_uses_dynamic_stack 0
		.amdhsa_enable_private_segment 0
		.amdhsa_system_sgpr_workgroup_id_x 1
		.amdhsa_system_sgpr_workgroup_id_y 0
		.amdhsa_system_sgpr_workgroup_id_z 0
		.amdhsa_system_sgpr_workgroup_info 0
		.amdhsa_system_vgpr_workitem_id 2
		.amdhsa_next_free_vgpr 256
		.amdhsa_next_free_sgpr 102
		.amdhsa_accum_offset 256
		.amdhsa_reserve_vcc 1
		.amdhsa_float_round_mode_32 0
		.amdhsa_float_round_mode_16_64 0
		.amdhsa_float_denorm_mode_32 3
		.amdhsa_float_denorm_mode_16_64 3
		.amdhsa_dx10_clamp 1
		.amdhsa_ieee_mode 1
		.amdhsa_fp16_overflow 0
		.amdhsa_tg_split 0
		.amdhsa_exception_fp_ieee_invalid_op 0
		.amdhsa_exception_fp_denorm_src 0
		.amdhsa_exception_fp_ieee_div_zero 0
		.amdhsa_exception_fp_ieee_overflow 0
		.amdhsa_exception_fp_ieee_underflow 0
		.amdhsa_exception_fp_ieee_inexact 0
		.amdhsa_exception_int_div_zero 0
	.end_amdhsa_kernel

; __global__ void __launch_bounds__(NWAVES * 64, 2) fwd_kernel(Args a) {
amdhsa.kernels:
  - .agpr_count:     0
    .args:
      - .offset:         0
        .size:           176
        .value_kind:     by_value
      - .offset:         176
        .size:           4
        .value_kind:     hidden_block_count_x
      - .offset:         180
        .size:           4
        .value_kind:     hidden_block_count_y
      - .offset:         184
        .size:           4
        .value_kind:     hidden_block_count_z
      - .offset:         188
        .size:           2
        .value_kind:     hidden_group_size_x
      - .offset:         190
        .size:           2
        .value_kind:     hidden_group_size_y
      - .offset:         192
        .size:           2
        .value_kind:     hidden_group_size_z
      - .offset:         194
        .size:           2
        .value_kind:     hidden_remainder_x
      - .offset:         196
        .size:           2
        .value_kind:     hidden_remainder_y
      - .offset:         198
        .size:           2
        .value_kind:     hidden_remainder_z
      - .offset:         216
        .size:           8
        .value_kind:     hidden_global_offset_x
      - .offset:         224
        .size:           8
        .value_kind:     hidden_global_offset_y
      - .offset:         232
        .size:           8
        .value_kind:     hidden_global_offset_z
      - .offset:         240
        .size:           2
        .value_kind:     hidden_grid_dims
      - .offset:         264
        .size:           8
        .value_kind:     hidden_multigrid_sync_arg
      - .offset:         296
        .size:           4
        .value_kind:     hidden_dynamic_lds_size
    .group_segment_fixed_size: 0
    .kernarg_segment_align: 8
    .kernarg_segment_size: 432
    .language:       OpenCL C
    .language_version:
      - 2
      - 0
    .max_flat_workgroup_size: 512
    .name:           _Z10fwd_kernel4Args
    .private_segment_fixed_size: 0
    .sgpr_count:     108
    .sgpr_spill_count: 27
    .symbol:         _Z10fwd_kernel4Args.kd
    .uniform_work_group_size: 1
    .uses_dynamic_stack: false
    .vgpr_count:     256
    .vgpr_spill_count: 0
    .wavefront_size: 64
